# u5 plus s_setprio 1 for the MFMA stretch after each in-loop barrier and s_setprio 0 before the staging vmcnt ladder, in all four GEMM main loops
# speedup vs baseline: 1.0133x; 1.0108x over previous
; DI void gemm_128_deep(const bf16_t* __restrict__ A, int lda, const bf16_t* __restrict__ B, int ldb, int K, f32x16 (&acc)[2][2], bf16_t* sA, bf16_t* sBunused) {
;     ...
;   GL_P(0)
;   GL_Q(64)
;   __syncthreads();
;   ST_LDS(0, pa0, pa1, pa2, pa3, pb0, pb1, pb2, pb3)
;   GL_P(128)
;   __syncthreads();
;   for (int k0 = 0; k0 < K - 256; k0 += 128) {
;     MMA_TILE(0)
;     ST_LDS(1, qa0, qa1, qa2, qa3, qb0, qb1, qb2, qb3)
;     GL_Q(k0 + 192)
;     __syncthreads();
;     MMA_TILE(1)
;     ST_LDS(0, pa0, pa1, pa2, pa3, pb0, pb1, pb2, pb3)
;     GL_P(k0 + 256)
;     __syncthreads();
;   }
.LBB0_208:
	ds_read_b128 v[168:171], v128
	ds_read_b128 v[172:175], v129 offset:18432
	ds_read_b128 v[176:179], v128 offset:32
	ds_read_b128 v[180:183], v129 offset:18464
	ds_read_b128 v[184:187], v129 offset:23040
	ds_read_b128 v[188:191], v129 offset:23072
	s_mov_b32 s45, 0x1304000
	s_waitcnt lgkmcnt(4)
	v_mfma_f32_32x32x16_bf16 v[48:63], v[168:171], v[172:175], v[48:63]
	s_mov_b32 s46, 0x1324000
	s_mov_b32 s47, 0x1344000
	s_mov_b32 s48, 0x1364000
	s_addk_i32 s43, 0x80
	s_cmpk_lt_u32 s43, 0x680
	s_waitcnt lgkmcnt(1)
	v_mfma_f32_32x32x16_bf16 v[32:47], v[168:171], v[184:187], v[32:47]
	ds_read_b128 v[168:171], v128 offset:4608
	ds_read_b128 v[192:195], v128 offset:4640
	s_waitcnt lgkmcnt(1)
	v_mfma_f32_32x32x16_bf16 v[16:31], v[168:171], v[172:175], v[16:31]
	v_mfma_f32_32x32x16_bf16 v[0:15], v[168:171], v[184:187], v[0:15]
	v_mfma_f32_32x32x16_bf16 v[48:63], v[176:179], v[180:183], v[48:63]
	v_mfma_f32_32x32x16_bf16 v[32:47], v[176:179], v[188:191], v[32:47]
	s_waitcnt lgkmcnt(0)
	v_mfma_f32_32x32x16_bf16 v[16:31], v[192:195], v[180:183], v[16:31]
	ds_read_b128 v[168:171], v129 offset:18496
	ds_read_b128 v[172:175], v128 offset:64
	ds_read_b128 v[176:179], v128 offset:96
	ds_read_b128 v[180:183], v128 offset:4672
	ds_read_b128 v[184:187], v128 offset:4704
	v_mfma_f32_32x32x16_bf16 v[0:15], v[192:195], v[188:191], v[0:15]
	ds_read_b128 v[188:191], v129 offset:18528
	ds_read_b128 v[192:195], v129 offset:23104
	ds_read_b128 v[196:199], v129 offset:23136
	s_setprio 0
	s_waitcnt vmcnt(15)
	ds_write_b128 v130, v[96:99] offset:36864
	s_waitcnt vmcnt(14)
	ds_write_b128 v130, v[100:103] offset:41472
	s_waitcnt vmcnt(13)
	ds_write_b128 v130, v[104:107] offset:46080
	s_waitcnt vmcnt(12)
	ds_write_b128 v130, v[108:111] offset:50688
	v_lshl_add_u64 v[96:97], v[150:151], 0, v[156:157]
	v_add_co_u32_e32 v152, vcc, s83, v96
	v_lshl_add_u64 v[98:99], v[148:149], 0, v[156:157]
	s_nop 0
	v_addc_co_u32_e32 v153, vcc, 0, v97, vcc
	v_add_co_u32_e32 v200, vcc, s84, v96
	s_waitcnt lgkmcnt(10)
	v_mfma_f32_32x32x16_bf16 v[48:63], v[172:175], v[168:171], v[48:63]
	v_addc_co_u32_e32 v201, vcc, 0, v97, vcc
	v_add_co_u32_e32 v202, vcc, s85, v96
	s_waitcnt vmcnt(11)
	ds_write_b128 v130, v[112:115] offset:55296
	s_waitcnt vmcnt(10)
	ds_write_b128 v130, v[116:119] offset:59904
	s_waitcnt vmcnt(9)
	ds_write_b128 v130, v[120:123] offset:64512
	s_waitcnt vmcnt(8)
	ds_write_b128 v131, v[124:127] offset:13824
	v_addc_co_u32_e32 v203, vcc, 0, v97, vcc
	s_waitcnt lgkmcnt(9)
	v_mfma_f32_32x32x16_bf16 v[32:47], v[172:175], v[192:195], v[32:47]
	v_add_co_u32_e32 v204, vcc, s86, v96
	v_lshl_add_u64 v[148:149], v[148:149], 0, s[94:95]
	s_nop 0
	v_addc_co_u32_e32 v205, vcc, 0, v97, vcc
	v_add_co_u32_e32 v206, vcc, s45, v98
	v_mfma_f32_32x32x16_bf16 v[16:31], v[180:183], v[168:171], v[16:31]
	s_nop 0
	v_addc_co_u32_e32 v207, vcc, 0, v99, vcc
	v_add_co_u32_e32 v208, vcc, s46, v98
	v_lshl_add_u64 v[150:151], v[150:151], 0, s[94:95]
	s_nop 0
	v_addc_co_u32_e32 v209, vcc, 0, v99, vcc
	v_mfma_f32_32x32x16_bf16 v[0:15], v[180:183], v[192:195], v[0:15]
	v_add_co_u32_e32 v210, vcc, s47, v98
	s_nop 1
	v_addc_co_u32_e32 v211, vcc, 0, v99, vcc
	v_add_co_u32_e32 v212, vcc, s48, v98
	v_mfma_f32_32x32x16_bf16 v[48:63], v[176:179], v[188:191], v[48:63]
	s_nop 0
	v_addc_co_u32_e32 v213, vcc, 0, v99, vcc
	global_load_dwordx4 v[96:99], v[152:153], off offset:2176
	global_load_dwordx4 v[100:103], v[200:201], off offset:2176
	global_load_dwordx4 v[104:107], v[202:203], off offset:2176
	global_load_dwordx4 v[108:111], v[204:205], off offset:2176
	global_load_dwordx4 v[112:115], v[206:207], off offset:2176
	global_load_dwordx4 v[116:119], v[208:209], off offset:2176
	global_load_dwordx4 v[120:123], v[210:211], off offset:2176
	global_load_dwordx4 v[124:127], v[212:213], off offset:2176
	s_waitcnt lgkmcnt(0)
	s_barrier
	s_setprio 1
	v_mfma_f32_32x32x16_bf16 v[32:47], v[176:179], v[196:199], v[32:47]
	ds_read_b128 v[168:171], v128 offset:36864
	ds_read_b128 v[172:175], v129 offset:55296
	ds_read_b128 v[176:179], v128 offset:36896
	ds_read_b128 v[180:183], v129 offset:55328
	v_mfma_f32_32x32x16_bf16 v[16:31], v[184:187], v[188:191], v[16:31]
	v_mfma_f32_32x32x16_bf16 v[0:15], v[184:187], v[196:199], v[0:15]
	ds_read_b128 v[184:187], v129 offset:59904
	ds_read_b128 v[188:191], v129 offset:59936
	s_waitcnt lgkmcnt(4)
	v_mfma_f32_32x32x16_bf16 v[48:63], v[168:171], v[172:175], v[48:63]
	s_waitcnt lgkmcnt(1)
	v_mfma_f32_32x32x16_bf16 v[32:47], v[168:171], v[184:187], v[32:47]
	ds_read_b128 v[168:171], v128 offset:41472
	ds_read_b128 v[192:195], v128 offset:41504
	s_waitcnt lgkmcnt(1)
	v_mfma_f32_32x32x16_bf16 v[16:31], v[168:171], v[172:175], v[16:31]
	v_mfma_f32_32x32x16_bf16 v[0:15], v[168:171], v[184:187], v[0:15]
	v_mfma_f32_32x32x16_bf16 v[48:63], v[176:179], v[180:183], v[48:63]
	v_mfma_f32_32x32x16_bf16 v[32:47], v[176:179], v[188:191], v[32:47]
	s_waitcnt lgkmcnt(0)
	v_mfma_f32_32x32x16_bf16 v[16:31], v[192:195], v[180:183], v[16:31]
	ds_read_b128 v[168:171], v128 offset:36928
	ds_read_b128 v[172:175], v129 offset:55360
	ds_read_b128 v[176:179], v128 offset:36960
	ds_read_b128 v[180:183], v129 offset:55392
	v_mfma_f32_32x32x16_bf16 v[0:15], v[192:195], v[188:191], v[0:15]
	ds_read_b128 v[184:187], v129 offset:59968
	ds_read_b128 v[188:191], v129 offset:60000
	s_waitcnt lgkmcnt(4)
	v_mfma_f32_32x32x16_bf16 v[48:63], v[168:171], v[172:175], v[48:63]
	s_waitcnt lgkmcnt(1)
	v_mfma_f32_32x32x16_bf16 v[32:47], v[168:171], v[184:187], v[32:47]
	ds_read_b128 v[168:171], v128 offset:41536
	ds_read_b128 v[192:195], v128 offset:41568
	s_setprio 0
	s_waitcnt vmcnt(13)
	ds_write_b128 v130, v[92:95]
	ds_write_b128 v130, v[64:67] offset:4608
	ds_write_b128 v130, v[68:71] offset:9216
	s_waitcnt vmcnt(11)
	ds_write_b128 v130, v[84:87] offset:13824
	ds_write_b128 v130, v[72:75] offset:18432
	s_waitcnt vmcnt(10)
	ds_write_b128 v130, v[76:79] offset:23040
	s_waitcnt vmcnt(9)
	ds_write_b128 v130, v[80:83] offset:27648
	s_waitcnt vmcnt(8)
	ds_write_b128 v130, v[88:91] offset:32256
	global_load_dwordx4 v[92:95], v[152:153], off offset:2304
	global_load_dwordx4 v[64:67], v[200:201], off offset:2304
	global_load_dwordx4 v[68:71], v[202:203], off offset:2304
	global_load_dwordx4 v[84:87], v[204:205], off offset:2304
	global_load_dwordx4 v[72:75], v[206:207], off offset:2304
	global_load_dwordx4 v[76:79], v[208:209], off offset:2304
	global_load_dwordx4 v[80:83], v[210:211], off offset:2304
	global_load_dwordx4 v[88:91], v[212:213], off offset:2304
	s_waitcnt lgkmcnt(0)
	s_barrier
; DI void gemm_128_deep(const bf16_t* __restrict__ A, int lda, const bf16_t* __restrict__ B, int ldb, int K, f32x16 (&acc)[2][2], bf16_t* sA, bf16_t* sBunused) {
;     ...
;   for (int k0 = 0; k0 < K - 256; k0 += 128) {
;     MMA_TILE(0)
;     ST_LDS(1, qa0, qa1, qa2, qa3, qb0, qb1, qb2, qb3)
;     GL_Q(k0 + 192)
;     __syncthreads();
;     MMA_TILE(1)
;     ST_LDS(0, pa0, pa1, pa2, pa3, pb0, pb1, pb2, pb3)
;     GL_P(k0 + 256)
;     __syncthreads();
;   }
;   MMA_TILE(0)
;   ST_LDS(1, qa0, qa1, qa2, qa3, qb0, qb1, qb2, qb3)
;   GL_Q(K - 64)
;   __syncthreads();
;   MMA_TILE(1)
;   ST_LDS(0, pa0, pa1, pa2, pa3, pb0, pb1, pb2, pb3)
;   __syncthreads();
;   MMA_TILE(0)
	s_setprio 1
	v_mfma_f32_32x32x16_bf16 v[16:31], v[168:171], v[172:175], v[16:31]
	v_mfma_f32_32x32x16_bf16 v[0:15], v[168:171], v[184:187], v[0:15]
	v_mfma_f32_32x32x16_bf16 v[48:63], v[176:179], v[180:183], v[48:63]
	v_mfma_f32_32x32x16_bf16 v[32:47], v[176:179], v[188:191], v[32:47]
	v_mfma_f32_32x32x16_bf16 v[16:31], v[192:195], v[180:183], v[16:31]
	v_mfma_f32_32x32x16_bf16 v[0:15], v[192:195], v[188:191], v[0:15]
	s_cbranch_scc1 .LBB0_208
	s_setprio 0
	ds_read_b128 v[148:151], v128
	ds_read_b128 v[168:171], v129 offset:18432
	ds_read_b128 v[172:175], v129 offset:23040
	s_mov_b64 s[52:53], -1
	s_cmp_gt_i32 s60, 15
	s_waitcnt lgkmcnt(1)
	v_mfma_f32_32x32x16_bf16 v[48:63], v[148:151], v[168:171], v[48:63]
	s_waitcnt lgkmcnt(0)
	v_mfma_f32_32x32x16_bf16 v[32:47], v[148:151], v[172:175], v[32:47]
	ds_read_b128 v[148:151], v128 offset:4608
	s_waitcnt lgkmcnt(0)
	v_mfma_f32_32x32x16_bf16 v[16:31], v[148:151], v[168:171], v[16:31]
	v_mfma_f32_32x32x16_bf16 v[0:15], v[148:151], v[172:175], v[0:15]
	ds_read_b128 v[148:151], v128 offset:32
	ds_read_b128 v[168:171], v129 offset:18464
	ds_read_b128 v[172:175], v129 offset:23072
	s_waitcnt lgkmcnt(1)
	v_mfma_f32_32x32x16_bf16 v[48:63], v[148:151], v[168:171], v[48:63]
	s_waitcnt lgkmcnt(0)
	v_mfma_f32_32x32x16_bf16 v[32:47], v[148:151], v[172:175], v[32:47]
	ds_read_b128 v[148:151], v128 offset:4640
	s_waitcnt lgkmcnt(0)
	v_mfma_f32_32x32x16_bf16 v[16:31], v[148:151], v[168:171], v[16:31]
	v_mfma_f32_32x32x16_bf16 v[0:15], v[148:151], v[172:175], v[0:15]
	ds_read_b128 v[148:151], v128 offset:64
	ds_read_b128 v[168:171], v129 offset:18496
	ds_read_b128 v[172:175], v129 offset:23104
	s_waitcnt lgkmcnt(1)
	v_mfma_f32_32x32x16_bf16 v[48:63], v[148:151], v[168:171], v[48:63]
	s_waitcnt lgkmcnt(0)
	v_mfma_f32_32x32x16_bf16 v[32:47], v[148:151], v[172:175], v[32:47]
	ds_read_b128 v[148:151], v128 offset:4672
	s_waitcnt lgkmcnt(0)
	v_mfma_f32_32x32x16_bf16 v[16:31], v[148:151], v[168:171], v[16:31]
	v_mfma_f32_32x32x16_bf16 v[0:15], v[148:151], v[172:175], v[0:15]
	ds_read_b128 v[148:151], v128 offset:96
	ds_read_b128 v[168:171], v129 offset:18528
	ds_read_b128 v[172:175], v129 offset:23136
	s_waitcnt lgkmcnt(1)
	v_mfma_f32_32x32x16_bf16 v[48:63], v[148:151], v[168:171], v[48:63]
	s_waitcnt lgkmcnt(0)
	v_mfma_f32_32x32x16_bf16 v[32:47], v[148:151], v[172:175], v[32:47]
	ds_read_b128 v[148:151], v128 offset:4704
	s_waitcnt vmcnt(15)
	ds_write_b128 v130, v[96:99] offset:36864
	s_waitcnt vmcnt(14)
	ds_write_b128 v130, v[100:103] offset:41472
	s_waitcnt vmcnt(13)
	ds_write_b128 v130, v[104:107] offset:46080
	s_waitcnt vmcnt(12)
	ds_write_b128 v130, v[108:111] offset:50688
	s_waitcnt vmcnt(11)
	ds_write_b128 v130, v[112:115] offset:55296
	s_waitcnt vmcnt(10)
	ds_write_b128 v130, v[116:119] offset:59904
	s_waitcnt vmcnt(9)
	ds_write_b128 v130, v[120:123] offset:64512
	s_waitcnt vmcnt(8)
	ds_write_b128 v131, v[124:127] offset:13824
	global_load_dwordx4 v[96:99], v[142:143], off offset:3968
	global_load_dwordx4 v[100:103], v[138:139], off offset:3968
	global_load_dwordx4 v[104:107], v[144:145], off offset:3968
	global_load_dwordx4 v[108:111], v[146:147], off offset:3968
	global_load_dwordx4 v[112:115], v[132:133], off offset:3968
	global_load_dwordx4 v[116:119], v[134:135], off offset:3968
	global_load_dwordx4 v[120:123], v[136:137], off offset:3968
	global_load_dwordx4 v[124:127], v[140:141], off offset:3968
	s_waitcnt lgkmcnt(0)
	s_barrier
	ds_read_b128 v[132:135], v128 offset:36864
	ds_read_b128 v[136:139], v129 offset:55296
	ds_read_b128 v[140:143], v129 offset:59904
	s_waitcnt lgkmcnt(1)
	v_mfma_f32_32x32x16_bf16 v[48:63], v[132:135], v[136:139], v[48:63]
	s_waitcnt lgkmcnt(0)
	v_mfma_f32_32x32x16_bf16 v[32:47], v[132:135], v[140:143], v[32:47]
	ds_read_b128 v[132:135], v128 offset:41472
	v_mfma_f32_32x32x16_bf16 v[16:31], v[148:151], v[168:171], v[16:31]
	v_mfma_f32_32x32x16_bf16 v[0:15], v[148:151], v[172:175], v[0:15]
	s_waitcnt lgkmcnt(0)
	v_mfma_f32_32x32x16_bf16 v[16:31], v[132:135], v[136:139], v[16:31]
	v_mfma_f32_32x32x16_bf16 v[0:15], v[132:135], v[140:143], v[0:15]
	ds_read_b128 v[132:135], v128 offset:36896
	ds_read_b128 v[136:139], v129 offset:55328
	ds_read_b128 v[140:143], v129 offset:59936
	s_waitcnt lgkmcnt(1)
	v_mfma_f32_32x32x16_bf16 v[48:63], v[132:135], v[136:139], v[48:63]
	s_waitcnt lgkmcnt(0)
	v_mfma_f32_32x32x16_bf16 v[32:47], v[132:135], v[140:143], v[32:47]
	ds_read_b128 v[132:135], v128 offset:41504
	s_waitcnt lgkmcnt(0)
	v_mfma_f32_32x32x16_bf16 v[16:31], v[132:135], v[136:139], v[16:31]
	v_mfma_f32_32x32x16_bf16 v[0:15], v[132:135], v[140:143], v[0:15]
	ds_read_b128 v[132:135], v128 offset:36928
	ds_read_b128 v[136:139], v129 offset:55360
	ds_read_b128 v[140:143], v129 offset:59968
	s_waitcnt lgkmcnt(1)
	v_mfma_f32_32x32x16_bf16 v[48:63], v[132:135], v[136:139], v[48:63]
	s_waitcnt lgkmcnt(0)
	v_mfma_f32_32x32x16_bf16 v[32:47], v[132:135], v[140:143], v[32:47]
	ds_read_b128 v[132:135], v128 offset:41536
	s_waitcnt lgkmcnt(0)
	v_mfma_f32_32x32x16_bf16 v[16:31], v[132:135], v[136:139], v[16:31]
	v_mfma_f32_32x32x16_bf16 v[0:15], v[132:135], v[140:143], v[0:15]
	ds_read_b128 v[132:135], v128 offset:36960
	ds_read_b128 v[136:139], v129 offset:55392
	ds_read_b128 v[140:143], v129 offset:60000
	s_waitcnt lgkmcnt(1)
	v_mfma_f32_32x32x16_bf16 v[48:63], v[132:135], v[136:139], v[48:63]
	s_waitcnt lgkmcnt(0)
	v_mfma_f32_32x32x16_bf16 v[32:47], v[132:135], v[140:143], v[32:47]
	ds_read_b128 v[132:135], v128 offset:41568
	s_waitcnt vmcnt(15)
	ds_write_b128 v130, v[92:95]
	s_waitcnt vmcnt(14)
	ds_write_b128 v130, v[64:67] offset:4608
	s_waitcnt vmcnt(13)
	ds_write_b128 v130, v[68:71] offset:9216
	s_waitcnt vmcnt(12)
	ds_write_b128 v130, v[84:87] offset:13824
	s_waitcnt vmcnt(11)
	ds_write_b128 v130, v[72:75] offset:18432
	s_waitcnt vmcnt(10)
	ds_write_b128 v130, v[76:79] offset:23040
	s_waitcnt vmcnt(9)
	ds_write_b128 v130, v[80:83] offset:27648
	s_waitcnt vmcnt(8)
	ds_write_b128 v130, v[88:91] offset:32256
	s_waitcnt lgkmcnt(0)
	s_barrier
; DI void gemm_128_deep(const bf16_t* __restrict__ A, int lda, const bf16_t* __restrict__ B, int ldb, int K, f32x16 (&acc)[2][2], bf16_t* sA, bf16_t* sBunused) {
;     ...
;   MMA_TILE(0)
;   ST_LDS(1, qa0, qa1, qa2, qa3, qb0, qb1, qb2, qb3)
;   GL_Q(K - 64)
;   __syncthreads();
;   MMA_TILE(1)
;   ST_LDS(0, pa0, pa1, pa2, pa3, pb0, pb1, pb2, pb3)
;   __syncthreads();
;   MMA_TILE(0)
;   ST_LDS(1, qa0, qa1, qa2, qa3, qb0, qb1, qb2, qb3)
;   __syncthreads();
;   MMA_TILE(1)
;   __syncthreads();
	ds_read_b128 v[64:67], v128
	ds_read_b128 v[68:71], v129 offset:18432
	ds_read_b128 v[72:75], v129 offset:23040
	s_waitcnt lgkmcnt(1)
	v_mfma_f32_32x32x16_bf16 v[48:63], v[64:67], v[68:71], v[48:63]
	s_waitcnt lgkmcnt(0)
	v_mfma_f32_32x32x16_bf16 v[32:47], v[64:67], v[72:75], v[32:47]
	ds_read_b128 v[64:67], v128 offset:4608
	v_mfma_f32_32x32x16_bf16 v[16:31], v[132:135], v[136:139], v[16:31]
	v_mfma_f32_32x32x16_bf16 v[0:15], v[132:135], v[140:143], v[0:15]
	s_waitcnt lgkmcnt(0)
	v_mfma_f32_32x32x16_bf16 v[16:31], v[64:67], v[68:71], v[16:31]
	v_mfma_f32_32x32x16_bf16 v[0:15], v[64:67], v[72:75], v[0:15]
	ds_read_b128 v[64:67], v128 offset:32
	ds_read_b128 v[68:71], v129 offset:18464
	ds_read_b128 v[72:75], v129 offset:23072
	s_waitcnt lgkmcnt(1)
	v_mfma_f32_32x32x16_bf16 v[48:63], v[64:67], v[68:71], v[48:63]
	s_waitcnt lgkmcnt(0)
	v_mfma_f32_32x32x16_bf16 v[32:47], v[64:67], v[72:75], v[32:47]
	ds_read_b128 v[64:67], v128 offset:4640
	s_waitcnt lgkmcnt(0)
	v_mfma_f32_32x32x16_bf16 v[16:31], v[64:67], v[68:71], v[16:31]
	v_mfma_f32_32x32x16_bf16 v[0:15], v[64:67], v[72:75], v[0:15]
	ds_read_b128 v[64:67], v128 offset:64
	ds_read_b128 v[68:71], v129 offset:18496
	ds_read_b128 v[72:75], v129 offset:23104
	s_waitcnt lgkmcnt(1)
	v_mfma_f32_32x32x16_bf16 v[48:63], v[64:67], v[68:71], v[48:63]
	s_waitcnt lgkmcnt(0)
	v_mfma_f32_32x32x16_bf16 v[32:47], v[64:67], v[72:75], v[32:47]
	ds_read_b128 v[64:67], v128 offset:4672
	s_waitcnt lgkmcnt(0)
	v_mfma_f32_32x32x16_bf16 v[16:31], v[64:67], v[68:71], v[16:31]
	v_mfma_f32_32x32x16_bf16 v[0:15], v[64:67], v[72:75], v[0:15]
	ds_read_b128 v[64:67], v128 offset:96
	ds_read_b128 v[68:71], v129 offset:18528
	ds_read_b128 v[72:75], v129 offset:23136
	s_waitcnt lgkmcnt(1)
	v_mfma_f32_32x32x16_bf16 v[48:63], v[64:67], v[68:71], v[48:63]
	s_waitcnt lgkmcnt(0)
	v_mfma_f32_32x32x16_bf16 v[32:47], v[64:67], v[72:75], v[32:47]
	ds_read_b128 v[64:67], v128 offset:4704
	s_waitcnt vmcnt(7)
	ds_write_b128 v130, v[96:99] offset:36864
	s_waitcnt vmcnt(6)
	ds_write_b128 v130, v[100:103] offset:41472
	s_waitcnt vmcnt(5)
	ds_write_b128 v130, v[104:107] offset:46080
	s_waitcnt vmcnt(4)
	ds_write_b128 v130, v[108:111] offset:50688
	s_waitcnt vmcnt(3)
	ds_write_b128 v130, v[112:115] offset:55296
	s_waitcnt vmcnt(2)
	ds_write_b128 v130, v[116:119] offset:59904
	s_waitcnt vmcnt(1)
	ds_write_b128 v130, v[120:123] offset:64512
	s_waitcnt vmcnt(0)
	ds_write_b128 v131, v[124:127] offset:13824
	s_waitcnt lgkmcnt(0)
	s_barrier
	v_mfma_f32_32x32x16_bf16 v[16:31], v[64:67], v[68:71], v[16:31]
	v_mfma_f32_32x32x16_bf16 v[0:15], v[64:67], v[72:75], v[0:15]
	ds_read_b128 v[64:67], v128 offset:36864
	ds_read_b128 v[68:71], v129 offset:55296
	ds_read_b128 v[72:75], v129 offset:59904
	s_waitcnt lgkmcnt(1)
	v_mfma_f32_32x32x16_bf16 v[48:63], v[64:67], v[68:71], v[48:63]
	s_waitcnt lgkmcnt(0)
	v_mfma_f32_32x32x16_bf16 v[32:47], v[64:67], v[72:75], v[32:47]
	ds_read_b128 v[64:67], v128 offset:41472
	s_waitcnt lgkmcnt(0)
	v_mfma_f32_32x32x16_bf16 v[16:31], v[64:67], v[68:71], v[16:31]
	v_mfma_f32_32x32x16_bf16 v[0:15], v[64:67], v[72:75], v[0:15]
	ds_read_b128 v[64:67], v128 offset:36896
	ds_read_b128 v[68:71], v129 offset:55328
	ds_read_b128 v[72:75], v129 offset:59936
	s_waitcnt lgkmcnt(1)
	v_mfma_f32_32x32x16_bf16 v[48:63], v[64:67], v[68:71], v[48:63]
	s_waitcnt lgkmcnt(0)
	v_mfma_f32_32x32x16_bf16 v[32:47], v[64:67], v[72:75], v[32:47]
	ds_read_b128 v[64:67], v128 offset:41504
	s_waitcnt lgkmcnt(0)
	v_mfma_f32_32x32x16_bf16 v[16:31], v[64:67], v[68:71], v[16:31]
	v_mfma_f32_32x32x16_bf16 v[0:15], v[64:67], v[72:75], v[0:15]
	ds_read_b128 v[64:67], v128 offset:36928
	ds_read_b128 v[68:71], v129 offset:55360
	ds_read_b128 v[72:75], v129 offset:59968
	s_waitcnt lgkmcnt(1)
	v_mfma_f32_32x32x16_bf16 v[48:63], v[64:67], v[68:71], v[48:63]
	s_waitcnt lgkmcnt(0)
	v_mfma_f32_32x32x16_bf16 v[32:47], v[64:67], v[72:75], v[32:47]
	ds_read_b128 v[64:67], v128 offset:41536
	s_waitcnt lgkmcnt(0)
	v_mfma_f32_32x32x16_bf16 v[16:31], v[64:67], v[68:71], v[16:31]
	v_mfma_f32_32x32x16_bf16 v[0:15], v[64:67], v[72:75], v[0:15]
	ds_read_b128 v[64:67], v128 offset:36960
	ds_read_b128 v[68:71], v129 offset:55392
	ds_read_b128 v[72:75], v129 offset:60000
	s_waitcnt lgkmcnt(1)
	v_mfma_f32_32x32x16_bf16 v[48:63], v[64:67], v[68:71], v[48:63]
	s_waitcnt lgkmcnt(0)
	v_mfma_f32_32x32x16_bf16 v[32:47], v[64:67], v[72:75], v[32:47]
	ds_read_b128 v[64:67], v128 offset:41568
	s_waitcnt lgkmcnt(0)
	s_barrier
	v_mfma_f32_32x32x16_bf16 v[16:31], v[64:67], v[68:71], v[16:31]
	v_mfma_f32_32x32x16_bf16 v[0:15], v[64:67], v[72:75], v[0:15]
	s_cbranch_scc1 .LBB0_213
	s_andn2_b64 vcc, exec, s[52:53]
	s_cbranch_vccz .LBB0_225

; DI void gemm_128_2set(const bf16_t* __restrict__ A, int lda, const bf16_t* __restrict__ B, int ldb, int K, f32x16 (&acc)[2][2], bf16_t* sA, bf16_t* sB) {
;     ...
;   for (int k0 = 0; k0 < K - 128; k0 += 128) {
;     __syncthreads();
;     ST2(pa0, pa1, pa2, pa3, pb0, pb1, pb2, pb3)
;     __syncthreads();
;     GL2_P(k0 + 128)
;     MMA2()
;     __syncthreads();
;     ST2(qa0, qa1, qa2, qa3, qb0, qb1, qb2, qb3)
;     __syncthreads();
;     GL2_Q(k0 + 192)
;     MMA2()
;   }
.LBB0_881:
	s_barrier
	s_setprio 1
	s_setprio 0
	s_waitcnt vmcnt(12)
	ds_write_b128 v184, v[108:111]
	ds_write_b128 v184, v[96:99] offset:4608
	ds_write_b128 v184, v[100:103] offset:9216
	ds_write_b128 v184, v[104:107] offset:13824
	s_waitcnt vmcnt(11)
	ds_write_b128 v184, v[112:115] offset:18432
	s_waitcnt vmcnt(10)
	ds_write_b128 v184, v[116:119] offset:23040
	s_waitcnt vmcnt(9)
	ds_write_b128 v184, v[120:123] offset:27648
	s_waitcnt vmcnt(8)
	ds_write_b128 v184, v[124:127] offset:32256
	s_waitcnt lgkmcnt(0)
	s_barrier
	s_setprio 1
	ds_read_b128 v[96:99], v128
	ds_read_b128 v[100:103], v129 offset:18432
	ds_read_b128 v[104:107], v128 offset:32
	ds_read_b128 v[108:111], v129 offset:18464
	ds_read_b128 v[112:115], v129 offset:23040
	ds_read_b128 v[116:119], v129 offset:23072
	s_waitcnt lgkmcnt(4)
	v_mfma_f32_32x32x16_bf16 v[48:63], v[96:99], v[100:103], v[48:63]
	s_mov_b32 s55, 0x19864000
	v_lshl_add_u64 v[202:203], v[130:131], 0, v[156:157]
	v_lshl_add_u64 v[204:205], v[138:139], 0, v[156:157]
	v_lshl_add_u64 v[206:207], v[134:135], 0, v[156:157]
	v_lshl_add_u64 v[208:209], v[136:137], 0, v[156:157]
	s_addk_i32 s54, 0x80
	v_lshl_add_u64 v[130:131], v[130:131], 0, s[94:95]
	s_waitcnt lgkmcnt(1)
	v_mfma_f32_32x32x16_bf16 v[32:47], v[96:99], v[112:115], v[32:47]
	ds_read_b128 v[96:99], v128 offset:4608
	ds_read_b128 v[120:123], v128 offset:4640
	v_lshl_add_u64 v[134:135], v[134:135], 0, s[94:95]
	v_lshl_add_u64 v[136:137], v[136:137], 0, s[94:95]
	s_cmpk_lt_u32 s54, 0x100
	v_lshl_add_u64 v[138:139], v[138:139], 0, s[94:95]
	s_waitcnt lgkmcnt(1)
	v_mfma_f32_32x32x16_bf16 v[16:31], v[96:99], v[100:103], v[16:31]
	v_mfma_f32_32x32x16_bf16 v[0:15], v[96:99], v[112:115], v[0:15]
	ds_read_b128 v[96:99], v128 offset:64
	ds_read_b128 v[100:103], v129 offset:18496
	ds_read_b128 v[186:189], v128 offset:96
	ds_read_b128 v[190:193], v129 offset:18528
	v_mfma_f32_32x32x16_bf16 v[48:63], v[104:107], v[108:111], v[48:63]
	v_mfma_f32_32x32x16_bf16 v[32:47], v[104:107], v[116:119], v[32:47]
	s_waitcnt lgkmcnt(4)
	v_mfma_f32_32x32x16_bf16 v[16:31], v[120:123], v[108:111], v[16:31]
	v_mfma_f32_32x32x16_bf16 v[0:15], v[120:123], v[116:119], v[0:15]
	ds_read_b128 v[112:115], v129 offset:23104
	ds_read_b128 v[116:119], v128 offset:4672
	ds_read_b128 v[194:197], v129 offset:23136
	ds_read_b128 v[198:201], v128 offset:4704
	v_lshl_add_u64 v[120:121], v[132:133], 0, v[156:157]
	v_add_co_u32_e32 v210, vcc, s55, v120
	s_mov_b32 s55, 0x1986c000
	s_nop 0
	v_addc_co_u32_e32 v211, vcc, 0, v121, vcc
	s_waitcnt lgkmcnt(6)
	v_mfma_f32_32x32x16_bf16 v[48:63], v[96:99], v[100:103], v[48:63]
	v_add_co_u32_e32 v212, vcc, s55, v120
	s_mov_b32 s55, 0x19874000
	s_nop 0
	v_addc_co_u32_e32 v213, vcc, 0, v121, vcc
	v_add_co_u32_e32 v226, vcc, s55, v120
	s_waitcnt lgkmcnt(3)
	v_mfma_f32_32x32x16_bf16 v[32:47], v[96:99], v[112:115], v[32:47]
	v_addc_co_u32_e32 v227, vcc, 0, v121, vcc
	s_mov_b32 s55, 0x1987c000
	v_add_co_u32_e32 v238, vcc, s55, v120
	global_load_dwordx4 v[108:111], v[202:203], off offset:256
	s_nop 0
	v_addc_co_u32_e32 v239, vcc, 0, v121, vcc
	s_waitcnt lgkmcnt(2)
	v_mfma_f32_32x32x16_bf16 v[16:31], v[116:119], v[100:103], v[16:31]
	global_load_dwordx4 v[96:99], v[204:205], off offset:256
	global_load_dwordx4 v[100:103], v[206:207], off offset:256
	global_load_dwordx4 v[104:107], v[208:209], off offset:256
	v_lshl_add_u64 v[132:133], v[132:133], 0, s[94:95]
	v_mfma_f32_32x32x16_bf16 v[0:15], v[116:119], v[112:115], v[0:15]
	global_load_dwordx4 v[112:115], v[210:211], off offset:2048
	global_load_dwordx4 v[116:119], v[212:213], off offset:2048
	global_load_dwordx4 v[120:123], v[226:227], off offset:2048
	global_load_dwordx4 v[124:127], v[238:239], off offset:2048
	s_waitcnt lgkmcnt(0)
	s_barrier
	s_setprio 1
	s_setprio 0
	s_waitcnt vmcnt(15)
	ds_write_b128 v184, v[64:67]
	s_waitcnt vmcnt(14)
	ds_write_b128 v184, v[68:71] offset:4608
	s_waitcnt vmcnt(13)
	ds_write_b128 v184, v[72:75] offset:9216
	s_waitcnt vmcnt(12)
	ds_write_b128 v184, v[80:83] offset:13824
	s_waitcnt vmcnt(11)
	ds_write_b128 v184, v[76:79] offset:18432
	s_waitcnt vmcnt(10)
	ds_write_b128 v184, v[84:87] offset:23040
	s_waitcnt vmcnt(9)
	ds_write_b128 v184, v[88:91] offset:27648
	s_waitcnt vmcnt(8)
	ds_write_b128 v184, v[92:95] offset:32256
	s_waitcnt lgkmcnt(0)
	v_mfma_f32_32x32x16_bf16 v[48:63], v[186:189], v[190:193], v[48:63]
	s_barrier
; DI void gemm_128_2set(const bf16_t* __restrict__ A, int lda, const bf16_t* __restrict__ B, int ldb, int K, f32x16 (&acc)[2][2], bf16_t* sA, bf16_t* sB) {
;     ...
;   for (int k0 = 0; k0 < K - 128; k0 += 128) {
;     __syncthreads();
;     ST2(pa0, pa1, pa2, pa3, pb0, pb1, pb2, pb3)
;     __syncthreads();
;     GL2_P(k0 + 128)
;     MMA2()
;     __syncthreads();
;     ST2(qa0, qa1, qa2, qa3, qb0, qb1, qb2, qb3)
;     __syncthreads();
;     GL2_Q(k0 + 192)
;     MMA2()
;   }
;   __syncthreads();
;   ST2(pa0, pa1, pa2, pa3, pb0, pb1, pb2, pb3)
;   __syncthreads();
;   MMA2()
;   __syncthreads();
;   ST2(qa0, qa1, qa2, qa3, qb0, qb1, qb2, qb3)
;   __syncthreads();
;   MMA2()
	s_setprio 1
	ds_read_b128 v[64:67], v128
	ds_read_b128 v[68:71], v129 offset:18432
	ds_read_b128 v[72:75], v128 offset:32
	ds_read_b128 v[76:79], v129 offset:18464
	ds_read_b128 v[80:83], v129 offset:23040
	ds_read_b128 v[84:87], v129 offset:23072
	v_mfma_f32_32x32x16_bf16 v[32:47], v[186:189], v[194:197], v[32:47]
	v_mfma_f32_32x32x16_bf16 v[16:31], v[198:201], v[190:193], v[16:31]
	v_mfma_f32_32x32x16_bf16 v[0:15], v[198:201], v[194:197], v[0:15]
	s_waitcnt lgkmcnt(4)
	v_mfma_f32_32x32x16_bf16 v[48:63], v[64:67], v[68:71], v[48:63]
	s_waitcnt lgkmcnt(1)
	v_mfma_f32_32x32x16_bf16 v[32:47], v[64:67], v[80:83], v[32:47]
	ds_read_b128 v[64:67], v128 offset:4608
	ds_read_b128 v[88:91], v128 offset:4640
	s_waitcnt lgkmcnt(1)
	v_mfma_f32_32x32x16_bf16 v[16:31], v[64:67], v[68:71], v[16:31]
	v_mfma_f32_32x32x16_bf16 v[0:15], v[64:67], v[80:83], v[0:15]
	v_mfma_f32_32x32x16_bf16 v[48:63], v[72:75], v[76:79], v[48:63]
	v_mfma_f32_32x32x16_bf16 v[32:47], v[72:75], v[84:87], v[32:47]
	ds_read_b128 v[64:67], v128 offset:64
	ds_read_b128 v[68:71], v129 offset:18496
	ds_read_b128 v[72:75], v128 offset:96
	ds_read_b128 v[92:95], v129 offset:18528
	s_waitcnt lgkmcnt(4)
	v_mfma_f32_32x32x16_bf16 v[16:31], v[88:91], v[76:79], v[16:31]
	ds_read_b128 v[76:79], v129 offset:23104
	ds_read_b128 v[186:189], v129 offset:23136
	v_mfma_f32_32x32x16_bf16 v[0:15], v[88:91], v[84:87], v[0:15]
	s_waitcnt lgkmcnt(4)
	v_mfma_f32_32x32x16_bf16 v[48:63], v[64:67], v[68:71], v[48:63]
	s_waitcnt lgkmcnt(1)
	v_mfma_f32_32x32x16_bf16 v[32:47], v[64:67], v[76:79], v[32:47]
	ds_read_b128 v[64:67], v128 offset:4672
	ds_read_b128 v[190:193], v128 offset:4704
	s_waitcnt lgkmcnt(1)
	v_mfma_f32_32x32x16_bf16 v[16:31], v[64:67], v[68:71], v[16:31]
	v_mfma_f32_32x32x16_bf16 v[0:15], v[64:67], v[76:79], v[0:15]
	v_mfma_f32_32x32x16_bf16 v[48:63], v[72:75], v[92:95], v[48:63]
	v_mfma_f32_32x32x16_bf16 v[32:47], v[72:75], v[186:189], v[32:47]
	global_load_dwordx4 v[64:67], v[202:203], off offset:384
	global_load_dwordx4 v[68:71], v[204:205], off offset:384
	global_load_dwordx4 v[72:75], v[206:207], off offset:384
	global_load_dwordx4 v[80:83], v[208:209], off offset:384
	global_load_dwordx4 v[76:79], v[210:211], off offset:2176
	global_load_dwordx4 v[84:87], v[212:213], off offset:2176
	global_load_dwordx4 v[88:91], v[226:227], off offset:2176
	s_waitcnt lgkmcnt(0)
	v_mfma_f32_32x32x16_bf16 v[16:31], v[190:193], v[92:95], v[16:31]
	global_load_dwordx4 v[92:95], v[238:239], off offset:2176
	v_mfma_f32_32x32x16_bf16 v[0:15], v[190:193], v[186:189], v[0:15]
	s_cbranch_scc1 .LBB0_881
	s_setprio 0
	s_barrier
	s_waitcnt vmcnt(15)
	ds_write_b128 v184, v[108:111]
	s_waitcnt vmcnt(14)
	ds_write_b128 v184, v[96:99] offset:4608
	s_waitcnt vmcnt(13)
	ds_write_b128 v184, v[100:103] offset:9216
	s_waitcnt vmcnt(12)
	ds_write_b128 v184, v[104:107] offset:13824
	s_waitcnt vmcnt(11)
	ds_write_b128 v184, v[112:115] offset:18432
	s_waitcnt vmcnt(10)
	ds_write_b128 v184, v[116:119] offset:23040
	s_waitcnt vmcnt(9)
	ds_write_b128 v184, v[120:123] offset:27648
	s_waitcnt vmcnt(8)
	ds_write_b128 v184, v[124:127] offset:32256
	s_waitcnt lgkmcnt(0)
	s_barrier
	ds_read_b128 v[96:99], v128
	ds_read_b128 v[100:103], v129 offset:18432
	ds_read_b128 v[104:107], v128 offset:32
	ds_read_b128 v[108:111], v129 offset:18464
	ds_read_b128 v[112:115], v129 offset:23040
	ds_read_b128 v[116:119], v129 offset:23072
	s_waitcnt lgkmcnt(4)
	v_mfma_f32_32x32x16_bf16 v[48:63], v[96:99], v[100:103], v[48:63]
	s_lshl_b64 s[54:55], s[50:51], 12
	s_lshl_b64 s[52:53], s[52:53], 12
	s_add_u32 s52, s63, s52
	s_addc_u32 s53, s64, s53
	s_movk_i32 s51, 0xff80
	s_waitcnt lgkmcnt(1)
	v_mfma_f32_32x32x16_bf16 v[32:47], v[96:99], v[112:115], v[32:47]
	ds_read_b128 v[96:99], v128 offset:4608
	ds_read_b128 v[120:123], v128 offset:4640
	s_waitcnt lgkmcnt(1)
	v_mfma_f32_32x32x16_bf16 v[16:31], v[96:99], v[100:103], v[16:31]
	v_mfma_f32_32x32x16_bf16 v[0:15], v[96:99], v[112:115], v[0:15]
	v_mfma_f32_32x32x16_bf16 v[48:63], v[104:107], v[108:111], v[48:63]
	v_mfma_f32_32x32x16_bf16 v[32:47], v[104:107], v[116:119], v[32:47]
	s_waitcnt lgkmcnt(0)
	v_mfma_f32_32x32x16_bf16 v[16:31], v[120:123], v[108:111], v[16:31]
	ds_read_b128 v[96:99], v128 offset:64
	ds_read_b128 v[100:103], v129 offset:18496
	ds_read_b128 v[104:107], v128 offset:96
	ds_read_b128 v[108:111], v129 offset:18528
	v_mfma_f32_32x32x16_bf16 v[0:15], v[120:123], v[116:119], v[0:15]
	ds_read_b128 v[112:115], v129 offset:23104
	ds_read_b128 v[116:119], v129 offset:23136
	s_waitcnt lgkmcnt(4)
	v_mfma_f32_32x32x16_bf16 v[48:63], v[96:99], v[100:103], v[48:63]
	s_waitcnt lgkmcnt(1)
	v_mfma_f32_32x32x16_bf16 v[32:47], v[96:99], v[112:115], v[32:47]
	ds_read_b128 v[96:99], v128 offset:4672
	ds_read_b128 v[120:123], v128 offset:4704
	s_waitcnt lgkmcnt(0)
	s_barrier
	s_waitcnt vmcnt(7)
	ds_write_b128 v184, v[64:67]
	s_waitcnt vmcnt(6)
	ds_write_b128 v184, v[68:71] offset:4608
	s_waitcnt vmcnt(5)
	ds_write_b128 v184, v[72:75] offset:9216
	s_waitcnt vmcnt(4)
	ds_write_b128 v184, v[80:83] offset:13824
	s_waitcnt vmcnt(3)
	ds_write_b128 v184, v[76:79] offset:18432
	s_waitcnt vmcnt(2)
	ds_write_b128 v184, v[84:87] offset:23040
	s_waitcnt vmcnt(1)
	ds_write_b128 v184, v[88:91] offset:27648
	s_waitcnt vmcnt(0)
	ds_write_b128 v184, v[92:95] offset:32256
	s_waitcnt lgkmcnt(0)
	v_mfma_f32_32x32x16_bf16 v[16:31], v[96:99], v[100:103], v[16:31]
	s_barrier
; #define TIDX ltid()
; DI void gemm_128_2set(const bf16_t* __restrict__ A, int lda, const bf16_t* __restrict__ B, int ldb, int K, f32x16 (&acc)[2][2], bf16_t* sA, bf16_t* sB) {
;   const int tid = TIDX, lane = tid & 63, wid = tid >> 6, wm = wid >> 1, wn = wid & 1, r = lane & 31, h = lane >> 5;
;   const int lrow = tid >> 3, lkc = (tid & 7) * 8;
;   const bf16_t* ga = A + (size_t)lrow * lda + lkc;
;   const bf16_t* gb = B + (size_t)lrow * ldb + lkc;
;   uint4 pa0, pa1, pa2, pa3, pb0, pb1, pb2, pb3, qa0, qa1, qa2, qa3, qb0, qb1, qb2, qb3;
;     ...
;   GL2_P(0)
;   GL2_Q(64)
; DI void phase_merge(CP p, const Ptrs& w, int l, bf16_t* sA, bf16_t* sB, unsigned* sU) {
;     ...
;         f32x16 U[2][2];
;         zero_acc(U);
;         gemm_128_2set(ys + (size_t)m0 * lds_, lds_, up_t + (size_t)(br * 2048 + n0) * 512, 512, 512, U, sA, sB);
; #pragma unroll
;         for (int a = 0; a < 2; ++a)
; #pragma unroll
;           for (int c = 0; c < 2; ++c)
; #pragma unroll
;             for (int i = 0; i < 8; ++i) sU[((a * 2 + c) * 8 + i) * 256 + tid] = pack2(U[a][c][2 * i], U[a][c][2 * i + 1]);
;       }
;       f32x16 G[2][2];
;       zero_acc(G);
;       gemm_128_2set(w.H + (size_t)m0 * 2048, 2048, gate_t + (size_t)(br * 2048 + n0) * 2048, 2048, 2048, G, sA, sB);
	ds_read_b128 v[64:67], v128
	ds_read_b128 v[68:71], v129 offset:18432
	ds_read_b128 v[72:75], v128 offset:32
	ds_read_b128 v[76:79], v129 offset:18464
	ds_read_b128 v[80:83], v129 offset:23040
	ds_read_b128 v[84:87], v129 offset:23072
	v_mfma_f32_32x32x16_bf16 v[0:15], v[96:99], v[112:115], v[0:15]
	v_mfma_f32_32x32x16_bf16 v[48:63], v[104:107], v[108:111], v[48:63]
	v_mfma_f32_32x32x16_bf16 v[32:47], v[104:107], v[116:119], v[32:47]
	v_mfma_f32_32x32x16_bf16 v[16:31], v[120:123], v[108:111], v[16:31]
	v_mfma_f32_32x32x16_bf16 v[0:15], v[120:123], v[116:119], v[0:15]
	s_waitcnt lgkmcnt(4)
	v_mfma_f32_32x32x16_bf16 v[48:63], v[64:67], v[68:71], v[48:63]
	s_waitcnt lgkmcnt(1)
	v_mfma_f32_32x32x16_bf16 v[32:47], v[64:67], v[80:83], v[32:47]
	ds_read_b128 v[64:67], v128 offset:4608
	ds_read_b128 v[88:91], v128 offset:4640
	s_waitcnt lgkmcnt(1)
	v_mfma_f32_32x32x16_bf16 v[16:31], v[64:67], v[68:71], v[16:31]
	v_mfma_f32_32x32x16_bf16 v[0:15], v[64:67], v[80:83], v[0:15]
	v_mfma_f32_32x32x16_bf16 v[48:63], v[72:75], v[76:79], v[48:63]
	v_mfma_f32_32x32x16_bf16 v[32:47], v[72:75], v[84:87], v[32:47]
	s_waitcnt lgkmcnt(0)
	v_mfma_f32_32x32x16_bf16 v[16:31], v[88:91], v[76:79], v[16:31]
	ds_read_b128 v[64:67], v128 offset:64
	ds_read_b128 v[68:71], v129 offset:18496
	ds_read_b128 v[72:75], v128 offset:96
	ds_read_b128 v[76:79], v129 offset:18528
	v_mfma_f32_32x32x16_bf16 v[0:15], v[88:91], v[84:87], v[0:15]
	ds_read_b128 v[80:83], v129 offset:23104
	ds_read_b128 v[84:87], v128 offset:4672
	ds_read_b128 v[88:91], v128 offset:4704
	ds_read_b128 v[92:95], v129 offset:23136
	s_waitcnt lgkmcnt(6)
	v_mfma_f32_32x32x16_bf16 v[48:63], v[64:67], v[68:71], v[48:63]
	s_waitcnt lgkmcnt(3)
	v_mfma_f32_32x32x16_bf16 v[32:47], v[64:67], v[80:83], v[32:47]
	s_waitcnt lgkmcnt(2)
	v_mfma_f32_32x32x16_bf16 v[16:31], v[84:87], v[68:71], v[16:31]
	v_mfma_f32_32x32x16_bf16 v[0:15], v[84:87], v[80:83], v[0:15]
	v_mfma_f32_32x32x16_bf16 v[48:63], v[72:75], v[76:79], v[48:63]
	s_waitcnt lgkmcnt(0)
	v_mfma_f32_32x32x16_bf16 v[32:47], v[72:75], v[92:95], v[32:47]
	s_nop 9
	v_cvt_pk_bf16_f32 v48, v48, v49
	v_cvt_pk_bf16_f32 v49, v50, v51
	ds_write2st64_b32 v140, v48, v49 offset0:144 offset1:148
	v_cvt_pk_bf16_f32 v48, v52, v53
	v_cvt_pk_bf16_f32 v49, v54, v55
	ds_write2st64_b32 v140, v48, v49 offset0:152 offset1:156
	v_cvt_pk_bf16_f32 v48, v56, v57
	v_mfma_f32_32x32x16_bf16 v[16:31], v[88:91], v[76:79], v[16:31]
	v_cvt_pk_bf16_f32 v32, v32, v33
	v_cvt_pk_bf16_f32 v33, v34, v35
	ds_write2st64_b32 v140, v32, v33 offset0:176 offset1:180
	v_cvt_pk_bf16_f32 v32, v36, v37
	v_cvt_pk_bf16_f32 v33, v38, v39
	v_cvt_pk_bf16_f32 v49, v58, v59
	ds_write2st64_b32 v140, v32, v33 offset0:184 offset1:188
	v_mfma_f32_32x32x16_bf16 v[0:15], v[88:91], v[92:95], v[0:15]
	s_nop 3
	v_cvt_pk_bf16_f32 v16, v16, v17
	v_cvt_pk_bf16_f32 v17, v18, v19
	ds_write2st64_b32 v140, v16, v17 offset0:208 offset1:212
	v_cvt_pk_bf16_f32 v16, v20, v21
	v_cvt_pk_bf16_f32 v17, v22, v23
	v_cvt_pk_bf16_f32 v32, v40, v41
	v_cvt_pk_bf16_f32 v33, v42, v43
	s_nop 0
	v_cvt_pk_bf16_f32 v0, v0, v1
	v_cvt_pk_bf16_f32 v1, v2, v3
	ds_write2st64_b32 v140, v0, v1 offset0:240 offset1:244
	v_cvt_pk_bf16_f32 v0, v4, v5
	v_cvt_pk_bf16_f32 v1, v6, v7
	ds_write2st64_b32 v140, v16, v17 offset0:216 offset1:220
	v_cvt_pk_bf16_f32 v16, v24, v25
	v_cvt_pk_bf16_f32 v17, v26, v27
	ds_write2st64_b32 v140, v0, v1 offset0:248 offset1:252
	v_cvt_pk_bf16_f32 v0, v8, v9
	v_cvt_pk_bf16_f32 v1, v10, v11
	ds_write2st64_b32 v140, v48, v49 offset0:160 offset1:164
	v_cvt_pk_bf16_f32 v48, v60, v61
	v_cvt_pk_bf16_f32 v49, v62, v63
	ds_write2st64_b32 v140, v32, v33 offset0:192 offset1:196
	v_cvt_pk_bf16_f32 v32, v44, v45
	v_cvt_pk_bf16_f32 v33, v46, v47
	ds_write2st64_b32 v140, v16, v17 offset0:224 offset1:228
	v_cvt_pk_bf16_f32 v16, v28, v29
	v_cvt_pk_bf16_f32 v17, v30, v31
	ds_write2st64_b32 v141, v0, v1 offset0:112 offset1:116
	v_cvt_pk_bf16_f32 v0, v12, v13
	v_cvt_pk_bf16_f32 v1, v14, v15
	v_mov_b32_e32 v20, v214
	ds_write2st64_b32 v140, v48, v49 offset0:168 offset1:172
	ds_write2st64_b32 v140, v32, v33 offset0:200 offset1:204
	ds_write2st64_b32 v140, v16, v17 offset0:232 offset1:236
	ds_write2st64_b32 v141, v0, v1 offset0:120 offset1:124
	s_nop 0
	v_ashrrev_i32_e32 v0, 3, v20
	v_lshlrev_b32_e32 v1, 3, v20
	v_and_b32_e32 v6, 56, v1
	v_ashrrev_i32_e32 v1, 31, v0
	v_lshlrev_b64 v[2:3], 12, v[0:1]
	v_lshl_add_u64 v[4:5], s[40:41], 0, v[2:3]
	v_lshlrev_b32_e32 v156, 1, v6
	v_lshl_add_u64 v[4:5], v[4:5], 0, v[156:157]
	v_add_co_u32_e32 v8, vcc, s75, v4
	v_lshl_add_u64 v[6:7], s[52:53], 0, v[2:3]
	s_nop 0
	v_addc_co_u32_e32 v9, vcc, 0, v5, vcc
	v_add_co_u32_e32 v10, vcc, s80, v4
	v_lshl_add_u64 v[6:7], v[6:7], 0, v[156:157]
	s_nop 0
	v_addc_co_u32_e32 v11, vcc, 0, v5, vcc
	v_add_co_u32_e32 v12, vcc, s28, v4
	v_mul_lo_u32 v0, v0, s88
	s_nop 0
	v_addc_co_u32_e32 v13, vcc, 0, v5, vcc
	v_add_co_u32_e32 v14, vcc, s75, v6
	v_and_b32_e32 v1, 31, v20
	s_nop 0
	v_addc_co_u32_e32 v15, vcc, 0, v7, vcc
	v_add_co_u32_e32 v16, vcc, s80, v6
	v_lshl_add_u32 v134, v0, 1, v156
	s_nop 0
	v_addc_co_u32_e32 v17, vcc, 0, v7, vcc
	v_add_co_u32_e32 v18, vcc, s28, v6
	v_lshrrev_b32_e32 v0, 1, v20
	s_nop 0
	v_addc_co_u32_e32 v19, vcc, 0, v7, vcc
	global_load_dwordx4 v[96:99], v[4:5], off
	global_load_dwordx4 v[80:83], v[4:5], off offset:128
	global_load_dwordx4 v[100:103], v[8:9], off
	global_load_dwordx4 v[64:67], v[8:9], off offset:128
	global_load_dwordx4 v[104:107], v[10:11], off
	global_load_dwordx4 v[68:71], v[10:11], off offset:128
	global_load_dwordx4 v[108:111], v[12:13], off
	global_load_dwordx4 v[72:75], v[12:13], off offset:128
	global_load_dwordx4 v[112:115], v[6:7], off
; DI void gemm_128_2set(const bf16_t* __restrict__ A, int lda, const bf16_t* __restrict__ B, int ldb, int K, f32x16 (&acc)[2][2], bf16_t* sA, bf16_t* sB) {
;     ...
;   for (int k0 = 0; k0 < K - 128; k0 += 128) {
;     __syncthreads();
;     ST2(pa0, pa1, pa2, pa3, pb0, pb1, pb2, pb3)
;     __syncthreads();
;     GL2_P(k0 + 128)
;     MMA2()
;     __syncthreads();
;     ST2(qa0, qa1, qa2, qa3, qb0, qb1, qb2, qb3)
;     __syncthreads();
;     GL2_Q(k0 + 192)
;     MMA2()
;   }
; DI void zero_acc(f32x16 (&acc)[2][2]) {
; #pragma unroll
;   for (int a = 0; a < 2; ++a)
; #pragma unroll
;     for (int b = 0; b < 2; ++b)
; #pragma unroll
;       for (int i = 0; i < 16; ++i) acc[a][b][i] = 0.f;
; }
	global_load_dwordx4 v[76:79], v[6:7], off offset:128
	global_load_dwordx4 v[116:119], v[14:15], off
	global_load_dwordx4 v[84:87], v[14:15], off offset:128
	global_load_dwordx4 v[120:123], v[16:17], off
	global_load_dwordx4 v[88:91], v[16:17], off offset:128
	global_load_dwordx4 v[124:127], v[18:19], off
	global_load_dwordx4 v[92:95], v[18:19], off offset:128
	v_and_or_b32 v1, v0, s82, v1
	v_and_b32_e32 v0, 16, v0
	v_mad_u64_u32 v[128:129], s[52:53], v1, s81, v[0:1]
	v_and_b32_e32 v1, 0x5f, v20
	v_mad_u32_u24 v129, v1, s81, v0
	v_and_b32_e32 v0, 7, v20
	s_add_u32 s52, s2, s54
	v_lshlrev_b32_e32 v156, 4, v0
	s_addc_u32 s53, s3, s55
	v_mov_b32_e32 v0, 0
	v_lshl_add_u64 v[130:131], s[52:53], 0, v[2:3]
	v_lshl_add_u64 v[132:133], s[48:49], 0, v[2:3]
	v_mov_b32_e32 v1, v0
	v_mov_b32_e32 v2, v0
	v_mov_b32_e32 v3, v0
	v_mov_b32_e32 v4, v0
	v_mov_b32_e32 v5, v0
	v_mov_b32_e32 v6, v0
	v_mov_b32_e32 v7, v0
	v_mov_b32_e32 v8, v0
	v_mov_b32_e32 v9, v0
	v_mov_b32_e32 v10, v0
	v_mov_b32_e32 v11, v0
	v_mov_b32_e32 v12, v0
	v_mov_b32_e32 v13, v0
	v_mov_b32_e32 v14, v0
	v_mov_b32_e32 v15, v0
	v_mov_b32_e32 v16, v0
	v_mov_b32_e32 v17, v0
	v_mov_b32_e32 v18, v0
	v_mov_b32_e32 v19, v0
	v_mov_b32_e32 v20, v0
	v_mov_b32_e32 v21, v0
	v_mov_b32_e32 v22, v0
	v_mov_b32_e32 v23, v0
	v_mov_b32_e32 v24, v0
	v_mov_b32_e32 v25, v0
	v_mov_b32_e32 v26, v0
	v_mov_b32_e32 v27, v0
	v_mov_b32_e32 v28, v0
	v_mov_b32_e32 v29, v0
	v_mov_b32_e32 v30, v0
	v_mov_b32_e32 v31, v0
	v_mov_b32_e32 v32, v0
	v_mov_b32_e32 v33, v0
	v_mov_b32_e32 v34, v0
	v_mov_b32_e32 v35, v0
	v_mov_b32_e32 v36, v0
	v_mov_b32_e32 v37, v0
	v_mov_b32_e32 v38, v0
	v_mov_b32_e32 v39, v0
	v_mov_b32_e32 v40, v0
	v_mov_b32_e32 v41, v0
	v_mov_b32_e32 v42, v0
	v_mov_b32_e32 v43, v0
	v_mov_b32_e32 v44, v0
	v_mov_b32_e32 v45, v0
	v_mov_b32_e32 v46, v0
	v_mov_b32_e32 v47, v0
	v_mov_b32_e32 v48, v0
	v_mov_b32_e32 v49, v0
	v_mov_b32_e32 v50, v0
	v_mov_b32_e32 v51, v0
	v_mov_b32_e32 v52, v0
	v_mov_b32_e32 v53, v0
	v_mov_b32_e32 v54, v0
	v_mov_b32_e32 v55, v0
	v_mov_b32_e32 v56, v0
	v_mov_b32_e32 v57, v0
	v_mov_b32_e32 v58, v0
	v_mov_b32_e32 v59, v0
	v_mov_b32_e32 v60, v0
	v_mov_b32_e32 v61, v0
	v_mov_b32_e32 v62, v0
	v_mov_b32_e32 v63, v0
	s_waitcnt vmcnt(1)
.LBB0_883:
	s_waitcnt lgkmcnt(0)
	s_barrier
	s_setprio 1
	s_setprio 0
	s_waitcnt vmcnt(15)
	ds_write_b128 v134, v[96:99]
	s_waitcnt vmcnt(14)
	ds_write_b128 v134, v[100:103] offset:4608
	s_waitcnt vmcnt(13)
	ds_write_b128 v134, v[104:107] offset:9216
	s_waitcnt vmcnt(12)
	ds_write_b128 v134, v[108:111] offset:13824
	s_waitcnt vmcnt(11)
	ds_write_b128 v134, v[112:115] offset:18432
	s_waitcnt vmcnt(10)
	ds_write_b128 v134, v[116:119] offset:23040
	s_waitcnt vmcnt(9)
	ds_write_b128 v134, v[120:123] offset:27648
	s_waitcnt vmcnt(8)
	ds_write_b128 v134, v[124:127] offset:32256
	s_waitcnt lgkmcnt(0)
	s_barrier
	s_setprio 1
	ds_read_b128 v[96:99], v128
	ds_read_b128 v[100:103], v129 offset:18432
	ds_read_b128 v[104:107], v128 offset:32
	ds_read_b128 v[108:111], v129 offset:18464
	ds_read_b128 v[112:115], v129 offset:23040
	ds_read_b128 v[116:119], v129 offset:23072
	s_waitcnt lgkmcnt(4)
	v_mfma_f32_32x32x16_bf16 v[48:63], v[96:99], v[100:103], v[48:63]
	s_mov_b32 s52, 0x17864000
	s_addk_i32 s51, 0x80
	s_cmpk_lt_u32 s51, 0x700
	s_waitcnt lgkmcnt(1)
	v_mfma_f32_32x32x16_bf16 v[32:47], v[96:99], v[112:115], v[32:47]
	ds_read_b128 v[96:99], v128 offset:4608
	ds_read_b128 v[120:123], v128 offset:4640
	s_waitcnt lgkmcnt(1)
	v_mfma_f32_32x32x16_bf16 v[16:31], v[96:99], v[100:103], v[16:31]
	v_mfma_f32_32x32x16_bf16 v[0:15], v[96:99], v[112:115], v[0:15]
	v_lshl_add_u64 v[112:113], v[132:133], 0, v[156:157]
	ds_read_b128 v[96:99], v128 offset:4672
	ds_read_b128 v[100:103], v128 offset:64
	ds_read_b128 v[136:139], v128 offset:96
	v_add_co_u32_e32 v196, vcc, s83, v112
	v_lshl_add_u64 v[114:115], v[130:131], 0, v[156:157]
	s_nop 0
	v_addc_co_u32_e32 v197, vcc, 0, v113, vcc
	v_mfma_f32_32x32x16_bf16 v[48:63], v[104:107], v[108:111], v[48:63]
	v_add_co_u32_e32 v198, vcc, s84, v112
	v_lshl_add_u64 v[130:131], v[130:131], 0, s[94:95]
	s_nop 0
	v_addc_co_u32_e32 v199, vcc, 0, v113, vcc
	v_add_co_u32_e32 v200, vcc, s85, v112
	v_mfma_f32_32x32x16_bf16 v[32:47], v[104:107], v[116:119], v[32:47]
	s_nop 0
	v_addc_co_u32_e32 v201, vcc, 0, v113, vcc
	v_add_co_u32_e32 v202, vcc, s86, v112
	v_lshl_add_u64 v[132:133], v[132:133], 0, s[94:95]
	s_nop 0
	v_addc_co_u32_e32 v203, vcc, 0, v113, vcc
	s_waitcnt lgkmcnt(3)
	v_mfma_f32_32x32x16_bf16 v[16:31], v[120:123], v[108:111], v[16:31]
	ds_read_b128 v[184:187], v128 offset:4704
	ds_read_b128 v[104:107], v129 offset:18496
	ds_read_b128 v[188:191], v129 offset:18528
	ds_read_b128 v[108:111], v129 offset:23104
	ds_read_b128 v[192:195], v129 offset:23136
	v_add_co_u32_e32 v204, vcc, s52, v114
	s_mov_b32 s52, 0x17884000
	s_nop 0
	v_addc_co_u32_e32 v205, vcc, 0, v115, vcc
	v_add_co_u32_e32 v206, vcc, s52, v114
	v_mfma_f32_32x32x16_bf16 v[0:15], v[120:123], v[116:119], v[0:15]
	s_nop 0
	v_addc_co_u32_e32 v207, vcc, 0, v115, vcc
	s_mov_b32 s52, 0x178a4000
	v_add_co_u32_e32 v208, vcc, s52, v114
	s_mov_b32 s52, 0x178c4000
	s_nop 0
	v_addc_co_u32_e32 v209, vcc, 0, v115, vcc
	s_waitcnt lgkmcnt(3)
	v_mfma_f32_32x32x16_bf16 v[48:63], v[100:103], v[104:107], v[48:63]
	v_add_co_u32_e32 v210, vcc, s52, v114
	s_nop 1
	v_addc_co_u32_e32 v211, vcc, 0, v115, vcc
	s_waitcnt lgkmcnt(1)
	v_mfma_f32_32x32x16_bf16 v[32:47], v[100:103], v[108:111], v[32:47]
	v_mfma_f32_32x32x16_bf16 v[16:31], v[96:99], v[104:107], v[16:31]
	v_mfma_f32_32x32x16_bf16 v[0:15], v[96:99], v[108:111], v[0:15]
	global_load_dwordx4 v[96:99], v[196:197], off offset:2048
	global_load_dwordx4 v[100:103], v[198:199], off offset:2048
	global_load_dwordx4 v[104:107], v[200:201], off offset:2048
	global_load_dwordx4 v[108:111], v[202:203], off offset:2048
	global_load_dwordx4 v[112:115], v[204:205], off offset:2048
	global_load_dwordx4 v[116:119], v[206:207], off offset:2048
	global_load_dwordx4 v[120:123], v[208:209], off offset:2048
	global_load_dwordx4 v[124:127], v[210:211], off offset:2048
	s_waitcnt lgkmcnt(0)
	s_barrier
; DI void gemm_128_2set(const bf16_t* __restrict__ A, int lda, const bf16_t* __restrict__ B, int ldb, int K, f32x16 (&acc)[2][2], bf16_t* sA, bf16_t* sB) {
;     ...
;   for (int k0 = 0; k0 < K - 128; k0 += 128) {
;     __syncthreads();
;     ST2(pa0, pa1, pa2, pa3, pb0, pb1, pb2, pb3)
;     __syncthreads();
;     GL2_P(k0 + 128)
;     MMA2()
;     __syncthreads();
;     ST2(qa0, qa1, qa2, qa3, qb0, qb1, qb2, qb3)
;     __syncthreads();
;     GL2_Q(k0 + 192)
;     MMA2()
;   }
;   __syncthreads();
;   ST2(pa0, pa1, pa2, pa3, pb0, pb1, pb2, pb3)
;   __syncthreads();
;   MMA2()
;   __syncthreads();
;   ST2(qa0, qa1, qa2, qa3, qb0, qb1, qb2, qb3)
	s_setprio 1
	s_setprio 0
	s_waitcnt vmcnt(15)
	ds_write_b128 v134, v[80:83]
	s_waitcnt vmcnt(14)
	ds_write_b128 v134, v[64:67] offset:4608
	s_waitcnt vmcnt(13)
	ds_write_b128 v134, v[68:71] offset:9216
	s_waitcnt vmcnt(12)
	ds_write_b128 v134, v[72:75] offset:13824
	s_waitcnt vmcnt(11)
	ds_write_b128 v134, v[76:79] offset:18432
	s_waitcnt vmcnt(10)
	ds_write_b128 v134, v[84:87] offset:23040
	s_waitcnt vmcnt(9)
	ds_write_b128 v134, v[88:91] offset:27648
	s_waitcnt vmcnt(8)
	ds_write_b128 v134, v[92:95] offset:32256
	v_mfma_f32_32x32x16_bf16 v[48:63], v[136:139], v[188:191], v[48:63]
	s_waitcnt lgkmcnt(0)
	s_barrier
	s_setprio 1
	ds_read_b128 v[64:67], v128
	ds_read_b128 v[68:71], v129 offset:18432
	ds_read_b128 v[72:75], v128 offset:32
	ds_read_b128 v[76:79], v129 offset:18464
	ds_read_b128 v[80:83], v129 offset:23040
	ds_read_b128 v[84:87], v129 offset:23072
	v_mfma_f32_32x32x16_bf16 v[32:47], v[136:139], v[192:195], v[32:47]
	v_mfma_f32_32x32x16_bf16 v[16:31], v[184:187], v[188:191], v[16:31]
	v_mfma_f32_32x32x16_bf16 v[0:15], v[184:187], v[192:195], v[0:15]
	s_waitcnt lgkmcnt(4)
	v_mfma_f32_32x32x16_bf16 v[48:63], v[64:67], v[68:71], v[48:63]
	s_waitcnt lgkmcnt(1)
	v_mfma_f32_32x32x16_bf16 v[32:47], v[64:67], v[80:83], v[32:47]
	ds_read_b128 v[64:67], v128 offset:4608
	ds_read_b128 v[88:91], v128 offset:4640
	s_waitcnt lgkmcnt(1)
	v_mfma_f32_32x32x16_bf16 v[16:31], v[64:67], v[68:71], v[16:31]
	v_mfma_f32_32x32x16_bf16 v[0:15], v[64:67], v[80:83], v[0:15]
	v_mfma_f32_32x32x16_bf16 v[48:63], v[72:75], v[76:79], v[48:63]
	v_mfma_f32_32x32x16_bf16 v[32:47], v[72:75], v[84:87], v[32:47]
	ds_read_b128 v[64:67], v128 offset:64
	ds_read_b128 v[68:71], v129 offset:18496
	ds_read_b128 v[72:75], v128 offset:96
	ds_read_b128 v[92:95], v129 offset:18528
	s_waitcnt lgkmcnt(4)
	v_mfma_f32_32x32x16_bf16 v[16:31], v[88:91], v[76:79], v[16:31]
	ds_read_b128 v[76:79], v129 offset:23104
	ds_read_b128 v[136:139], v129 offset:23136
	v_mfma_f32_32x32x16_bf16 v[0:15], v[88:91], v[84:87], v[0:15]
	s_waitcnt lgkmcnt(4)
	v_mfma_f32_32x32x16_bf16 v[48:63], v[64:67], v[68:71], v[48:63]
	s_waitcnt lgkmcnt(1)
	v_mfma_f32_32x32x16_bf16 v[32:47], v[64:67], v[76:79], v[32:47]
	ds_read_b128 v[64:67], v128 offset:4672
	ds_read_b128 v[184:187], v128 offset:4704
	s_waitcnt lgkmcnt(1)
	v_mfma_f32_32x32x16_bf16 v[16:31], v[64:67], v[68:71], v[16:31]
	v_mfma_f32_32x32x16_bf16 v[0:15], v[64:67], v[76:79], v[0:15]
	v_mfma_f32_32x32x16_bf16 v[48:63], v[72:75], v[92:95], v[48:63]
	v_mfma_f32_32x32x16_bf16 v[32:47], v[72:75], v[136:139], v[32:47]
	global_load_dwordx4 v[80:83], v[196:197], off offset:2176
	global_load_dwordx4 v[64:67], v[198:199], off offset:2176
	global_load_dwordx4 v[68:71], v[200:201], off offset:2176
	global_load_dwordx4 v[72:75], v[202:203], off offset:2176
	global_load_dwordx4 v[76:79], v[204:205], off offset:2176
	global_load_dwordx4 v[84:87], v[206:207], off offset:2176
	global_load_dwordx4 v[88:91], v[208:209], off offset:2176
	s_waitcnt lgkmcnt(0)
	v_mfma_f32_32x32x16_bf16 v[16:31], v[184:187], v[92:95], v[16:31]
	global_load_dwordx4 v[92:95], v[210:211], off offset:2176
	v_mfma_f32_32x32x16_bf16 v[0:15], v[184:187], v[136:139], v[0:15]
	s_cbranch_scc1 .LBB0_883
	s_setprio 0
	s_barrier
	s_waitcnt vmcnt(15)
	ds_write_b128 v134, v[96:99]
	s_waitcnt vmcnt(14)
	ds_write_b128 v134, v[100:103] offset:4608
	s_waitcnt vmcnt(13)
	ds_write_b128 v134, v[104:107] offset:9216
	s_waitcnt vmcnt(12)
	ds_write_b128 v134, v[108:111] offset:13824
	s_waitcnt vmcnt(11)
	ds_write_b128 v134, v[112:115] offset:18432
	s_waitcnt vmcnt(10)
	ds_write_b128 v134, v[116:119] offset:23040
	s_waitcnt vmcnt(9)
	ds_write_b128 v134, v[120:123] offset:27648
	s_waitcnt vmcnt(8)
	ds_write_b128 v134, v[124:127] offset:32256
	s_waitcnt lgkmcnt(0)
	s_barrier
	ds_read_b128 v[96:99], v128 offset:4608
	ds_read_b128 v[100:103], v129 offset:23040
	ds_read_b128 v[104:107], v128
	ds_read_b128 v[108:111], v128 offset:32
	ds_read_b128 v[112:115], v129 offset:18432
	ds_read_b128 v[116:119], v129 offset:18464
	s_waitcnt lgkmcnt(1)
	v_mfma_f32_32x32x16_bf16 v[48:63], v[104:107], v[112:115], v[48:63]
	s_add_i32 s73, s73, 1
	s_addk_i32 s50, 0x800
	s_cmp_eq_u32 s73, 4
	v_mfma_f32_32x32x16_bf16 v[32:47], v[104:107], v[100:103], v[32:47]
	v_mfma_f32_32x32x16_bf16 v[16:31], v[96:99], v[112:115], v[16:31]
	v_mfma_f32_32x32x16_bf16 v[0:15], v[96:99], v[100:103], v[0:15]
	ds_read_b128 v[96:99], v128 offset:4640
	ds_read_b128 v[100:103], v129 offset:23072
	s_waitcnt lgkmcnt(2)
	v_mfma_f32_32x32x16_bf16 v[48:63], v[108:111], v[116:119], v[48:63]
	s_waitcnt lgkmcnt(0)
	v_mfma_f32_32x32x16_bf16 v[32:47], v[108:111], v[100:103], v[32:47]
	v_mfma_f32_32x32x16_bf16 v[16:31], v[96:99], v[116:119], v[16:31]
	v_mfma_f32_32x32x16_bf16 v[0:15], v[96:99], v[100:103], v[0:15]
	ds_read_b128 v[96:99], v128 offset:64
	ds_read_b128 v[100:103], v128 offset:4672
	ds_read_b128 v[104:107], v129 offset:18496
	ds_read_b128 v[108:111], v129 offset:23104
	s_waitcnt lgkmcnt(1)
	v_mfma_f32_32x32x16_bf16 v[48:63], v[96:99], v[104:107], v[48:63]
	s_waitcnt lgkmcnt(0)
	v_mfma_f32_32x32x16_bf16 v[32:47], v[96:99], v[108:111], v[32:47]
	v_mfma_f32_32x32x16_bf16 v[16:31], v[100:103], v[104:107], v[16:31]
	v_mfma_f32_32x32x16_bf16 v[0:15], v[100:103], v[108:111], v[0:15]
	ds_read_b128 v[96:99], v128 offset:96
	ds_read_b128 v[100:103], v128 offset:4704
	ds_read_b128 v[104:107], v129 offset:18528
	ds_read_b128 v[108:111], v129 offset:23136
	s_waitcnt lgkmcnt(0)
	s_barrier
; DI float sigmf(float x) { return __builtin_amdgcn_rcpf(1.f + __expf(-x)); }
; DI void gemm_128_2set(const bf16_t* __restrict__ A, int lda, const bf16_t* __restrict__ B, int ldb, int K, f32x16 (&acc)[2][2], bf16_t* sA, bf16_t* sB) {
;     ...
;   MMA2()
;   __syncthreads();
;   ST2(qa0, qa1, qa2, qa3, qb0, qb1, qb2, qb3)
;   __syncthreads();
;   MMA2()
; DI void phase_merge(CP p, const Ptrs& w, int l, bf16_t* sA, bf16_t* sB, unsigned* sU) {
;     ...
; #pragma unroll
;       for (int a = 0; a < 2; ++a)
; #pragma unroll
;         for (int c = 0; c < 2; ++c)
; #pragma unroll
;           for (int i = 0; i < 8; ++i) {
;             unsigned uv = sU[((a * 2 + c) * 8 + i) * 256 + tid];
;             float u0 = __uint_as_float(uv << 16), u1 = __uint_as_float(uv & 0xffff0000u);
;             const unsigned tv = totp[a][c][i];
;             float t0 = __uint_as_float(tv << 16) + sigmf(G[a][c][2 * i]) * u0;
;             float t1 = __uint_as_float(tv & 0xffff0000u) + sigmf(G[a][c][2 * i + 1]) * u1;
;             totp[a][c][i] = pack2(t0, t1);
;           }
	s_waitcnt vmcnt(7)
	ds_write_b128 v134, v[80:83]
	s_waitcnt vmcnt(6)
	ds_write_b128 v134, v[64:67] offset:4608
	s_waitcnt vmcnt(5)
	ds_write_b128 v134, v[68:71] offset:9216
	s_waitcnt vmcnt(4)
	ds_write_b128 v134, v[72:75] offset:13824
	s_waitcnt vmcnt(3)
	ds_write_b128 v134, v[76:79] offset:18432
	s_waitcnt vmcnt(2)
	ds_write_b128 v134, v[84:87] offset:23040
	s_waitcnt vmcnt(1)
	ds_write_b128 v134, v[88:91] offset:27648
	s_waitcnt vmcnt(0)
	ds_write_b128 v134, v[92:95] offset:32256
	s_waitcnt lgkmcnt(0)
	s_barrier
	v_mfma_f32_32x32x16_bf16 v[48:63], v[96:99], v[104:107], v[48:63]
	ds_read_b128 v[64:67], v128 offset:4608
	ds_read_b128 v[68:71], v129 offset:23040
	ds_read_b128 v[72:75], v128
	ds_read_b128 v[76:79], v128 offset:32
	ds_read_b128 v[80:83], v129 offset:18432
	ds_read_b128 v[84:87], v129 offset:18464
	v_mfma_f32_32x32x16_bf16 v[32:47], v[96:99], v[108:111], v[32:47]
	v_mfma_f32_32x32x16_bf16 v[16:31], v[100:103], v[104:107], v[16:31]
	v_mfma_f32_32x32x16_bf16 v[0:15], v[100:103], v[108:111], v[0:15]
	s_waitcnt lgkmcnt(1)
	v_mfma_f32_32x32x16_bf16 v[48:63], v[72:75], v[80:83], v[48:63]
	v_mfma_f32_32x32x16_bf16 v[32:47], v[72:75], v[68:71], v[32:47]
	v_mfma_f32_32x32x16_bf16 v[16:31], v[64:67], v[80:83], v[16:31]
	v_mfma_f32_32x32x16_bf16 v[0:15], v[64:67], v[68:71], v[0:15]
	ds_read_b128 v[64:67], v128 offset:4640
	ds_read_b128 v[68:71], v129 offset:23072
	s_waitcnt lgkmcnt(2)
	v_mfma_f32_32x32x16_bf16 v[48:63], v[76:79], v[84:87], v[48:63]
	s_waitcnt lgkmcnt(0)
	v_mfma_f32_32x32x16_bf16 v[32:47], v[76:79], v[68:71], v[32:47]
	v_mfma_f32_32x32x16_bf16 v[16:31], v[64:67], v[84:87], v[16:31]
	v_mfma_f32_32x32x16_bf16 v[0:15], v[64:67], v[68:71], v[0:15]
	ds_read_b128 v[64:67], v128 offset:64
	ds_read_b128 v[68:71], v128 offset:4672
	ds_read_b128 v[72:75], v129 offset:18496
	ds_read_b128 v[76:79], v129 offset:23104
	s_waitcnt lgkmcnt(1)
	v_mfma_f32_32x32x16_bf16 v[48:63], v[64:67], v[72:75], v[48:63]
	s_waitcnt lgkmcnt(0)
	v_mfma_f32_32x32x16_bf16 v[32:47], v[64:67], v[76:79], v[32:47]
	v_mfma_f32_32x32x16_bf16 v[16:31], v[68:71], v[72:75], v[16:31]
	v_mfma_f32_32x32x16_bf16 v[0:15], v[68:71], v[76:79], v[0:15]
	ds_read_b128 v[64:67], v128 offset:96
	ds_read_b128 v[68:71], v128 offset:4704
	ds_read_b128 v[72:75], v129 offset:18528
	ds_read_b128 v[76:79], v129 offset:23136
	s_waitcnt lgkmcnt(1)
	v_mfma_f32_32x32x16_bf16 v[48:63], v[64:67], v[72:75], v[48:63]
	s_waitcnt lgkmcnt(0)
	v_mfma_f32_32x32x16_bf16 v[32:47], v[64:67], v[76:79], v[32:47]
	s_nop 9
	v_mul_f32_e32 v48, 0xbfb8aa3b, v48
	v_mul_f32_e32 v49, 0xbfb8aa3b, v49
	v_exp_f32_e32 v48, v48
	v_exp_f32_e32 v49, v49
	v_mul_f32_e32 v50, 0xbfb8aa3b, v50
	v_mul_f32_e32 v51, 0xbfb8aa3b, v51
	v_exp_f32_e32 v50, v50
	v_exp_f32_e32 v51, v51
	ds_read2st64_b32 v[64:65], v140 offset0:144 offset1:148
	v_add_f32_e32 v48, 1.0, v48
	v_add_f32_e32 v49, 1.0, v49
	v_rcp_f32_e32 v48, v48
	v_rcp_f32_e32 v49, v49
	v_add_f32_e32 v50, 1.0, v50
	v_add_f32_e32 v51, 1.0, v51
	v_rcp_f32_e32 v50, v50
	v_rcp_f32_e32 v51, v51
	v_mfma_f32_32x32x16_bf16 v[16:31], v[68:71], v[72:75], v[16:31]
	s_waitcnt lgkmcnt(0)
	v_lshlrev_b32_e32 v66, 16, v64
	v_and_b32_e32 v67, 0xffff0000, v64
	v_lshlrev_b32_e32 v64, 16, v182
	v_mul_f32_e32 v32, 0xbfb8aa3b, v32
	v_mul_f32_e32 v33, 0xbfb8aa3b, v33
	v_exp_f32_e32 v32, v32
	v_exp_f32_e32 v33, v33
	v_mfma_f32_32x32x16_bf16 v[0:15], v[68:71], v[76:79], v[0:15]
	v_lshlrev_b32_e32 v68, 16, v183
	v_and_b32_e32 v69, 0xffff0000, v183
	v_fma_f32 v48, v48, v66, v68
	v_fma_f32 v49, v49, v67, v69
	v_mul_f32_e32 v34, 0xbfb8aa3b, v34
	v_cvt_pk_bf16_f32 v183, v48, v49
	v_lshlrev_b32_e32 v48, 16, v65
	v_and_b32_e32 v49, 0xffff0000, v65
	v_and_b32_e32 v65, 0xffff0000, v182
	v_pk_fma_f32 v[48:49], v[50:51], v[48:49], v[64:65]
	v_lshlrev_b32_e32 v64, 16, v181
	v_cvt_pk_bf16_f32 v182, v48, v49
	ds_read2st64_b32 v[48:49], v140 offset0:152 offset1:156
	v_and_b32_e32 v65, 0xffff0000, v181
	v_mul_f32_e32 v35, 0xbfb8aa3b, v35
	v_exp_f32_e32 v34, v34
	v_exp_f32_e32 v35, v35
	s_waitcnt lgkmcnt(0)
	v_lshlrev_b32_e32 v50, 16, v48
	v_and_b32_e32 v51, 0xffff0000, v48
	v_mul_f32_e32 v48, 0xbfb8aa3b, v52
	v_exp_f32_e32 v48, v48
	v_add_f32_e32 v32, 1.0, v32
	v_add_f32_e32 v33, 1.0, v33
	v_rcp_f32_e32 v32, v32
	v_add_f32_e32 v48, 1.0, v48
	v_rcp_f32_e32 v52, v48
	v_mul_f32_e32 v48, 0xbfb8aa3b, v53
	v_exp_f32_e32 v48, v48
	v_rcp_f32_e32 v33, v33
	v_add_f32_e32 v34, 1.0, v34
	v_add_f32_e32 v35, 1.0, v35
	v_add_f32_e32 v48, 1.0, v48
	v_rcp_f32_e32 v53, v48
	v_lshlrev_b32_e32 v48, 16, v49
	v_and_b32_e32 v49, 0xffff0000, v49
	v_rcp_f32_e32 v34, v34
	v_pk_fma_f32 v[50:51], v[52:53], v[50:51], v[64:65]
	v_mul_f32_e32 v53, 0xbfb8aa3b, v55
	v_cvt_pk_bf16_f32 v181, v50, v51
	v_mul_f32_e32 v51, 0xbfb8aa3b, v54
	v_exp_f32_e32 v51, v51
	v_exp_f32_e32 v53, v53
	v_lshlrev_b32_e32 v50, 16, v180
	v_rcp_f32_e32 v35, v35
	v_add_f32_e32 v51, 1.0, v51
	v_add_f32_e32 v53, 1.0, v53
	v_rcp_f32_e32 v52, v51
	v_rcp_f32_e32 v53, v53
	v_and_b32_e32 v51, 0xffff0000, v180
	v_mul_f32_e32 v16, 0xbfb8aa3b, v16
	v_mul_f32_e32 v17, 0xbfb8aa3b, v17
	v_pk_fma_f32 v[48:49], v[52:53], v[48:49], v[50:51]
	v_lshlrev_b32_e32 v52, 16, v179
	v_cvt_pk_bf16_f32 v180, v48, v49
	ds_read2st64_b32 v[48:49], v140 offset0:160 offset1:164
	v_and_b32_e32 v53, 0xffff0000, v179
	v_exp_f32_e32 v16, v16
	v_exp_f32_e32 v17, v17
	v_mul_f32_e32 v18, 0xbfb8aa3b, v18
	s_waitcnt lgkmcnt(0)
; DI float sigmf(float x) { return __builtin_amdgcn_rcpf(1.f + __expf(-x)); }
; DI void phase_merge(CP p, const Ptrs& w, int l, bf16_t* sA, bf16_t* sB, unsigned* sU) {
;     ...
;       for (int a = 0; a < 2; ++a)
; #pragma unroll
;         for (int c = 0; c < 2; ++c)
; #pragma unroll
;           for (int i = 0; i < 8; ++i) {
;             unsigned uv = sU[((a * 2 + c) * 8 + i) * 256 + tid];
;             float u0 = __uint_as_float(uv << 16), u1 = __uint_as_float(uv & 0xffff0000u);
;             const unsigned tv = totp[a][c][i];
;             float t0 = __uint_as_float(tv << 16) + sigmf(G[a][c][2 * i]) * u0;
;             float t1 = __uint_as_float(tv & 0xffff0000u) + sigmf(G[a][c][2 * i + 1]) * u1;
;             totp[a][c][i] = pack2(t0, t1);
;           }
	v_lshlrev_b32_e32 v50, 16, v48
	v_and_b32_e32 v51, 0xffff0000, v48
	v_mul_f32_e32 v48, 0xbfb8aa3b, v56
	v_exp_f32_e32 v48, v48
	v_mul_f32_e32 v19, 0xbfb8aa3b, v19
	v_exp_f32_e32 v18, v18
	v_exp_f32_e32 v19, v19
	v_add_f32_e32 v48, 1.0, v48
	v_rcp_f32_e32 v54, v48
	v_mul_f32_e32 v48, 0xbfb8aa3b, v57
	v_exp_f32_e32 v48, v48
	v_add_f32_e32 v16, 1.0, v16
	v_add_f32_e32 v17, 1.0, v17
	v_rcp_f32_e32 v16, v16
	v_add_f32_e32 v48, 1.0, v48
	v_rcp_f32_e32 v55, v48
	v_lshlrev_b32_e32 v48, 16, v49
	v_and_b32_e32 v49, 0xffff0000, v49
	v_rcp_f32_e32 v17, v17
	v_pk_fma_f32 v[50:51], v[54:55], v[50:51], v[52:53]
	v_mul_f32_e32 v53, 0xbfb8aa3b, v59
	v_cvt_pk_bf16_f32 v179, v50, v51
	v_mul_f32_e32 v51, 0xbfb8aa3b, v58
	v_exp_f32_e32 v51, v51
	v_exp_f32_e32 v53, v53
	v_lshlrev_b32_e32 v50, 16, v177
	v_add_f32_e32 v18, 1.0, v18
	v_add_f32_e32 v51, 1.0, v51
	v_add_f32_e32 v53, 1.0, v53
	v_rcp_f32_e32 v52, v51
	v_rcp_f32_e32 v53, v53
	v_and_b32_e32 v51, 0xffff0000, v177
	v_add_f32_e32 v19, 1.0, v19
	v_rcp_f32_e32 v18, v18
	v_pk_fma_f32 v[48:49], v[52:53], v[48:49], v[50:51]
	v_lshlrev_b32_e32 v52, 16, v178
	v_cvt_pk_bf16_f32 v177, v48, v49
	ds_read2st64_b32 v[48:49], v140 offset0:168 offset1:172
	v_and_b32_e32 v53, 0xffff0000, v178
	v_rcp_f32_e32 v19, v19
	v_mul_f32_e32 v0, 0xbfb8aa3b, v0
	v_mul_f32_e32 v1, 0xbfb8aa3b, v1
	s_waitcnt lgkmcnt(0)
	v_lshlrev_b32_e32 v50, 16, v48
	v_and_b32_e32 v51, 0xffff0000, v48
	v_mul_f32_e32 v48, 0xbfb8aa3b, v60
	v_exp_f32_e32 v48, v48
	v_exp_f32_e32 v0, v0
	v_exp_f32_e32 v1, v1
	v_mul_f32_e32 v2, 0xbfb8aa3b, v2
	v_add_f32_e32 v48, 1.0, v48
	v_rcp_f32_e32 v54, v48
	v_mul_f32_e32 v48, 0xbfb8aa3b, v61
	v_exp_f32_e32 v48, v48
	v_mul_f32_e32 v3, 0xbfb8aa3b, v3
	v_exp_f32_e32 v2, v2
	v_exp_f32_e32 v3, v3
	v_add_f32_e32 v48, 1.0, v48
	v_rcp_f32_e32 v55, v48
	v_lshlrev_b32_e32 v48, 16, v49
	v_and_b32_e32 v49, 0xffff0000, v49
	v_add_f32_e32 v0, 1.0, v0
	v_pk_fma_f32 v[50:51], v[54:55], v[50:51], v[52:53]
	v_mul_f32_e32 v53, 0xbfb8aa3b, v63
	v_cvt_pk_bf16_f32 v178, v50, v51
	v_mul_f32_e32 v51, 0xbfb8aa3b, v62
	v_exp_f32_e32 v51, v51
	v_exp_f32_e32 v53, v53
	v_lshlrev_b32_e32 v50, 16, v173
	v_add_f32_e32 v1, 1.0, v1
	v_add_f32_e32 v51, 1.0, v51
	v_add_f32_e32 v53, 1.0, v53
	v_rcp_f32_e32 v52, v51
	v_rcp_f32_e32 v53, v53
	v_and_b32_e32 v51, 0xffff0000, v173
	v_rcp_f32_e32 v0, v0
	v_rcp_f32_e32 v1, v1
	v_pk_fma_f32 v[48:49], v[52:53], v[48:49], v[50:51]
	v_lshlrev_b32_e32 v52, 16, v176
	v_cvt_pk_bf16_f32 v173, v48, v49
	ds_read2st64_b32 v[48:49], v140 offset0:176 offset1:180
	v_and_b32_e32 v53, 0xffff0000, v176
	v_add_f32_e32 v2, 1.0, v2
	v_add_f32_e32 v3, 1.0, v3
	v_rcp_f32_e32 v2, v2
	s_waitcnt lgkmcnt(0)
	v_lshlrev_b32_e32 v50, 16, v48
	v_and_b32_e32 v51, 0xffff0000, v48
	v_pk_fma_f32 v[32:33], v[32:33], v[50:51], v[52:53]
	v_lshlrev_b32_e32 v48, 16, v170
	v_cvt_pk_bf16_f32 v176, v32, v33
	v_lshlrev_b32_e32 v32, 16, v49
	v_and_b32_e32 v33, 0xffff0000, v49
	v_and_b32_e32 v49, 0xffff0000, v170
	v_pk_fma_f32 v[32:33], v[34:35], v[32:33], v[48:49]
	v_lshlrev_b32_e32 v48, 16, v175
	v_cvt_pk_bf16_f32 v170, v32, v33
	ds_read2st64_b32 v[32:33], v140 offset0:184 offset1:188
	v_and_b32_e32 v49, 0xffff0000, v175
	v_rcp_f32_e32 v3, v3
	s_waitcnt lgkmcnt(0)
	v_lshlrev_b32_e32 v34, 16, v32
	v_and_b32_e32 v35, 0xffff0000, v32
	v_mul_f32_e32 v32, 0xbfb8aa3b, v36
	v_exp_f32_e32 v32, v32
	s_nop 0
	v_add_f32_e32 v32, 1.0, v32
	v_rcp_f32_e32 v36, v32
	v_mul_f32_e32 v32, 0xbfb8aa3b, v37
	v_exp_f32_e32 v32, v32
	s_nop 0
	v_add_f32_e32 v32, 1.0, v32
	v_rcp_f32_e32 v37, v32
	v_lshlrev_b32_e32 v32, 16, v33
	v_and_b32_e32 v33, 0xffff0000, v33
	v_pk_fma_f32 v[34:35], v[36:37], v[34:35], v[48:49]
	s_nop 0
	v_cvt_pk_bf16_f32 v175, v34, v35
	v_mul_f32_e32 v35, 0xbfb8aa3b, v38
	v_mul_f32_e32 v37, 0xbfb8aa3b, v39
	v_exp_f32_e32 v35, v35
	v_exp_f32_e32 v37, v37
	v_lshlrev_b32_e32 v34, 16, v174
	v_add_f32_e32 v35, 1.0, v35
	v_add_f32_e32 v37, 1.0, v37
	v_rcp_f32_e32 v36, v35
	v_rcp_f32_e32 v37, v37
	v_and_b32_e32 v35, 0xffff0000, v174
	v_pk_fma_f32 v[32:33], v[36:37], v[32:33], v[34:35]
	s_nop 0
	v_cvt_pk_bf16_f32 v174, v32, v33
	ds_read2st64_b32 v[32:33], v140 offset0:192 offset1:196
	v_lshlrev_b32_e32 v36, 16, v172
	v_and_b32_e32 v37, 0xffff0000, v172
	s_waitcnt lgkmcnt(0)
	v_lshlrev_b32_e32 v34, 16, v32
	v_and_b32_e32 v35, 0xffff0000, v32
	v_mul_f32_e32 v32, 0xbfb8aa3b, v40
	v_exp_f32_e32 v32, v32
	s_nop 0
	v_add_f32_e32 v32, 1.0, v32
	v_rcp_f32_e32 v38, v32
	v_mul_f32_e32 v32, 0xbfb8aa3b, v41
	v_exp_f32_e32 v32, v32
	s_nop 0
	v_add_f32_e32 v32, 1.0, v32
	v_rcp_f32_e32 v39, v32
	v_lshlrev_b32_e32 v32, 16, v33
	v_and_b32_e32 v33, 0xffff0000, v33
	v_pk_fma_f32 v[34:35], v[38:39], v[34:35], v[36:37]
	s_nop 0
	v_cvt_pk_bf16_f32 v172, v34, v35
	v_mul_f32_e32 v35, 0xbfb8aa3b, v42
	v_mul_f32_e32 v37, 0xbfb8aa3b, v43
	v_exp_f32_e32 v35, v35
	v_exp_f32_e32 v37, v37
	v_lshlrev_b32_e32 v34, 16, v171
	v_add_f32_e32 v35, 1.0, v35
	v_add_f32_e32 v37, 1.0, v37
	v_rcp_f32_e32 v36, v35
	v_rcp_f32_e32 v37, v37
	v_and_b32_e32 v35, 0xffff0000, v171
	v_pk_fma_f32 v[32:33], v[36:37], v[32:33], v[34:35]
	s_nop 0
	v_cvt_pk_bf16_f32 v171, v32, v33
	ds_read2st64_b32 v[32:33], v140 offset0:200 offset1:204
	v_lshlrev_b32_e32 v36, 16, v169
	v_and_b32_e32 v37, 0xffff0000, v169
	s_waitcnt lgkmcnt(0)
; DI float sigmf(float x) { return __builtin_amdgcn_rcpf(1.f + __expf(-x)); }
; DI void phase_merge(CP p, const Ptrs& w, int l, bf16_t* sA, bf16_t* sB, unsigned* sU) {
;     ...
;       for (int a = 0; a < 2; ++a)
; #pragma unroll
;         for (int c = 0; c < 2; ++c)
; #pragma unroll
;           for (int i = 0; i < 8; ++i) {
;             unsigned uv = sU[((a * 2 + c) * 8 + i) * 256 + tid];
;             float u0 = __uint_as_float(uv << 16), u1 = __uint_as_float(uv & 0xffff0000u);
;             const unsigned tv = totp[a][c][i];
;             float t0 = __uint_as_float(tv << 16) + sigmf(G[a][c][2 * i]) * u0;
;             float t1 = __uint_as_float(tv & 0xffff0000u) + sigmf(G[a][c][2 * i + 1]) * u1;
;             totp[a][c][i] = pack2(t0, t1);
;           }
	v_lshlrev_b32_e32 v34, 16, v32
	v_and_b32_e32 v35, 0xffff0000, v32
	v_mul_f32_e32 v32, 0xbfb8aa3b, v44
	v_exp_f32_e32 v32, v32
	s_nop 0
	v_add_f32_e32 v32, 1.0, v32
	v_rcp_f32_e32 v38, v32
	v_mul_f32_e32 v32, 0xbfb8aa3b, v45
	v_exp_f32_e32 v32, v32
	s_nop 0
	v_add_f32_e32 v32, 1.0, v32
	v_rcp_f32_e32 v39, v32
	v_lshlrev_b32_e32 v32, 16, v33
	v_and_b32_e32 v33, 0xffff0000, v33
	v_pk_fma_f32 v[34:35], v[38:39], v[34:35], v[36:37]
	s_nop 0
	v_cvt_pk_bf16_f32 v169, v34, v35
	v_mul_f32_e32 v35, 0xbfb8aa3b, v46
	v_mul_f32_e32 v37, 0xbfb8aa3b, v47
	v_exp_f32_e32 v35, v35
	v_exp_f32_e32 v37, v37
	v_lshlrev_b32_e32 v34, 16, v168
	v_add_f32_e32 v35, 1.0, v35
	v_add_f32_e32 v37, 1.0, v37
	v_rcp_f32_e32 v36, v35
	v_rcp_f32_e32 v37, v37
	v_and_b32_e32 v35, 0xffff0000, v168
	v_pk_fma_f32 v[32:33], v[36:37], v[32:33], v[34:35]
	s_nop 0
	v_cvt_pk_bf16_f32 v168, v32, v33
	ds_read2st64_b32 v[32:33], v140 offset0:208 offset1:212
	v_lshlrev_b32_e32 v36, 16, v167
	v_and_b32_e32 v37, 0xffff0000, v167
	s_waitcnt lgkmcnt(0)
	v_lshlrev_b32_e32 v34, 16, v32
	v_and_b32_e32 v35, 0xffff0000, v32
	v_pk_fma_f32 v[16:17], v[16:17], v[34:35], v[36:37]
	v_lshlrev_b32_e32 v32, 16, v164
	v_cvt_pk_bf16_f32 v167, v16, v17
	v_lshlrev_b32_e32 v16, 16, v33
	v_and_b32_e32 v17, 0xffff0000, v33
	v_and_b32_e32 v33, 0xffff0000, v164
	v_pk_fma_f32 v[16:17], v[18:19], v[16:17], v[32:33]
	v_lshlrev_b32_e32 v32, 16, v163
	v_cvt_pk_bf16_f32 v164, v16, v17
	ds_read2st64_b32 v[16:17], v140 offset0:216 offset1:220
	v_and_b32_e32 v33, 0xffff0000, v163
	s_waitcnt lgkmcnt(0)
	v_lshlrev_b32_e32 v18, 16, v16
	v_and_b32_e32 v19, 0xffff0000, v16
	v_mul_f32_e32 v16, 0xbfb8aa3b, v20
	v_exp_f32_e32 v16, v16
	s_nop 0
	v_add_f32_e32 v16, 1.0, v16
	v_rcp_f32_e32 v20, v16
	v_mul_f32_e32 v16, 0xbfb8aa3b, v21
	v_exp_f32_e32 v16, v16
	s_nop 0
	v_add_f32_e32 v16, 1.0, v16
	v_rcp_f32_e32 v21, v16
	v_lshlrev_b32_e32 v16, 16, v17
	v_and_b32_e32 v17, 0xffff0000, v17
	v_pk_fma_f32 v[18:19], v[20:21], v[18:19], v[32:33]
	s_nop 0
	v_cvt_pk_bf16_f32 v163, v18, v19
	v_mul_f32_e32 v19, 0xbfb8aa3b, v22
	v_mul_f32_e32 v21, 0xbfb8aa3b, v23
	v_exp_f32_e32 v19, v19
	v_exp_f32_e32 v21, v21
	v_lshlrev_b32_e32 v18, 16, v161
	v_add_f32_e32 v19, 1.0, v19
	v_add_f32_e32 v21, 1.0, v21
	v_rcp_f32_e32 v20, v19
	v_rcp_f32_e32 v21, v21
	v_and_b32_e32 v19, 0xffff0000, v161
	v_pk_fma_f32 v[16:17], v[20:21], v[16:17], v[18:19]
	s_nop 0
	v_cvt_pk_bf16_f32 v161, v16, v17
	ds_read2st64_b32 v[16:17], v140 offset0:224 offset1:228
	v_lshlrev_b32_e32 v20, 16, v155
	v_and_b32_e32 v21, 0xffff0000, v155
	s_waitcnt lgkmcnt(0)
	v_lshlrev_b32_e32 v18, 16, v16
	v_and_b32_e32 v19, 0xffff0000, v16
	v_mul_f32_e32 v16, 0xbfb8aa3b, v24
	v_exp_f32_e32 v16, v16
	s_nop 0
	v_add_f32_e32 v16, 1.0, v16
	v_rcp_f32_e32 v22, v16
	v_mul_f32_e32 v16, 0xbfb8aa3b, v25
	v_exp_f32_e32 v16, v16
	s_nop 0
	v_add_f32_e32 v16, 1.0, v16
	v_rcp_f32_e32 v23, v16
	v_lshlrev_b32_e32 v16, 16, v17
	v_and_b32_e32 v17, 0xffff0000, v17
	v_pk_fma_f32 v[18:19], v[22:23], v[18:19], v[20:21]
	s_nop 0
	v_cvt_pk_bf16_f32 v155, v18, v19
	v_mul_f32_e32 v19, 0xbfb8aa3b, v26
	v_mul_f32_e32 v21, 0xbfb8aa3b, v27
	v_exp_f32_e32 v19, v19
	v_exp_f32_e32 v21, v21
	v_lshlrev_b32_e32 v18, 16, v154
	v_add_f32_e32 v19, 1.0, v19
	v_add_f32_e32 v21, 1.0, v21
	v_rcp_f32_e32 v20, v19
	v_rcp_f32_e32 v21, v21
	v_and_b32_e32 v19, 0xffff0000, v154
	v_pk_fma_f32 v[16:17], v[20:21], v[16:17], v[18:19]
	s_nop 0
	v_cvt_pk_bf16_f32 v154, v16, v17
	ds_read2st64_b32 v[16:17], v140 offset0:232 offset1:236
	v_lshlrev_b32_e32 v20, 16, v153
	v_and_b32_e32 v21, 0xffff0000, v153
	s_waitcnt lgkmcnt(0)
	v_lshlrev_b32_e32 v18, 16, v16
	v_and_b32_e32 v19, 0xffff0000, v16
	v_mul_f32_e32 v16, 0xbfb8aa3b, v28
	v_exp_f32_e32 v16, v16
	s_nop 0
	v_add_f32_e32 v16, 1.0, v16
	v_rcp_f32_e32 v22, v16
	v_mul_f32_e32 v16, 0xbfb8aa3b, v29
	v_exp_f32_e32 v16, v16
	s_nop 0
	v_add_f32_e32 v16, 1.0, v16
	v_rcp_f32_e32 v23, v16
	v_lshlrev_b32_e32 v16, 16, v17
	v_and_b32_e32 v17, 0xffff0000, v17
	v_pk_fma_f32 v[18:19], v[22:23], v[18:19], v[20:21]
	s_nop 0
	v_cvt_pk_bf16_f32 v153, v18, v19
	v_mul_f32_e32 v19, 0xbfb8aa3b, v30
	v_mul_f32_e32 v21, 0xbfb8aa3b, v31
	v_exp_f32_e32 v19, v19
	v_exp_f32_e32 v21, v21
	v_lshlrev_b32_e32 v18, 16, v152
	v_add_f32_e32 v19, 1.0, v19
	v_add_f32_e32 v21, 1.0, v21
	v_rcp_f32_e32 v20, v19
	v_rcp_f32_e32 v21, v21
	v_and_b32_e32 v19, 0xffff0000, v152
	v_pk_fma_f32 v[16:17], v[20:21], v[16:17], v[18:19]
	s_nop 0
	v_cvt_pk_bf16_f32 v152, v16, v17
	ds_read2st64_b32 v[16:17], v140 offset0:240 offset1:244
	v_lshlrev_b32_e32 v20, 16, v151
	v_and_b32_e32 v21, 0xffff0000, v151
	s_waitcnt lgkmcnt(0)
	v_lshlrev_b32_e32 v18, 16, v16
	v_and_b32_e32 v19, 0xffff0000, v16
	v_pk_fma_f32 v[0:1], v[0:1], v[18:19], v[20:21]
	v_lshlrev_b32_e32 v16, 16, v150
	v_cvt_pk_bf16_f32 v151, v0, v1
	v_lshlrev_b32_e32 v0, 16, v17
	v_and_b32_e32 v1, 0xffff0000, v17
	v_and_b32_e32 v17, 0xffff0000, v150
	v_pk_fma_f32 v[0:1], v[2:3], v[0:1], v[16:17]
	v_lshlrev_b32_e32 v16, 16, v149
	v_cvt_pk_bf16_f32 v150, v0, v1
	ds_read2st64_b32 v[0:1], v140 offset0:248 offset1:252
	v_and_b32_e32 v17, 0xffff0000, v149
	s_waitcnt lgkmcnt(0)
	v_lshlrev_b32_e32 v2, 16, v0
	v_and_b32_e32 v3, 0xffff0000, v0
	v_mul_f32_e32 v0, 0xbfb8aa3b, v4
	v_exp_f32_e32 v0, v0
	s_nop 0
	v_add_f32_e32 v0, 1.0, v0
	v_rcp_f32_e32 v4, v0
	v_mul_f32_e32 v0, 0xbfb8aa3b, v5
	v_exp_f32_e32 v0, v0
	s_nop 0
	v_add_f32_e32 v0, 1.0, v0
	v_rcp_f32_e32 v5, v0
	v_lshlrev_b32_e32 v0, 16, v1
	v_and_b32_e32 v1, 0xffff0000, v1
	v_pk_fma_f32 v[2:3], v[4:5], v[2:3], v[16:17]
	s_nop 0
	v_cvt_pk_bf16_f32 v149, v2, v3
	v_mul_f32_e32 v3, 0xbfb8aa3b, v6
	v_mul_f32_e32 v5, 0xbfb8aa3b, v7
	v_exp_f32_e32 v3, v3
	v_exp_f32_e32 v5, v5
	v_lshlrev_b32_e32 v2, 16, v148
	v_add_f32_e32 v3, 1.0, v3
	v_add_f32_e32 v5, 1.0, v5
	v_rcp_f32_e32 v4, v3
	v_rcp_f32_e32 v5, v5
	v_and_b32_e32 v3, 0xffff0000, v148
	v_pk_fma_f32 v[0:1], v[4:5], v[0:1], v[2:3]
	s_nop 0
	v_cvt_pk_bf16_f32 v148, v0, v1
	ds_read2st64_b32 v[0:1], v141 offset0:112 offset1:116
	v_lshlrev_b32_e32 v4, 16, v147
	v_and_b32_e32 v5, 0xffff0000, v147
	s_waitcnt lgkmcnt(0)
; DI float sigmf(float x) { return __builtin_amdgcn_rcpf(1.f + __expf(-x)); }
; DI int crow(int i, int h) { return (i & 3) + 8 * (i >> 2) + 4 * h; }
; DI void phase_merge(CP p, const Ptrs& w, int l, bf16_t* sA, bf16_t* sB, unsigned* sU) {
;     ...
; #pragma unroll
;       for (int a = 0; a < 2; ++a)
; #pragma unroll
;         for (int c = 0; c < 2; ++c)
; #pragma unroll
;           for (int i = 0; i < 8; ++i) {
;             unsigned uv = sU[((a * 2 + c) * 8 + i) * 256 + tid];
;             float u0 = __uint_as_float(uv << 16), u1 = __uint_as_float(uv & 0xffff0000u);
;             const unsigned tv = totp[a][c][i];
;             float t0 = __uint_as_float(tv << 16) + sigmf(G[a][c][2 * i]) * u0;
;             float t1 = __uint_as_float(tv & 0xffff0000u) + sigmf(G[a][c][2 * i + 1]) * u1;
;             totp[a][c][i] = pack2(t0, t1);
;           }
;     }
;     bf16_t* dst = w.R2;
; #pragma unroll
;     for (int mi = 0; mi < 2; ++mi)
; #pragma unroll
;       for (int ni = 0; ni < 2; ++ni)
; #pragma unroll
;         for (int i = 0; i < 16; ++i) {
;           int row = m0 + wm * 64 + mi * 32 + crow(i, h), col = n0 + wn * 64 + ni * 32 + r;
;           const unsigned tv = totp[mi][ni][i >> 1];
;           dst[(size_t)row * 2048 + col] = (bf16_t)((i & 1) ? (tv >> 16) : (tv & 0xffffu));
;         }
	v_lshlrev_b32_e32 v2, 16, v0
	v_and_b32_e32 v3, 0xffff0000, v0
	v_mul_f32_e32 v0, 0xbfb8aa3b, v8
	v_exp_f32_e32 v0, v0
	s_nop 0
	v_add_f32_e32 v0, 1.0, v0
	v_rcp_f32_e32 v6, v0
	v_mul_f32_e32 v0, 0xbfb8aa3b, v9
	v_exp_f32_e32 v0, v0
	s_nop 0
	v_add_f32_e32 v0, 1.0, v0
	v_rcp_f32_e32 v7, v0
	v_lshlrev_b32_e32 v0, 16, v1
	v_and_b32_e32 v1, 0xffff0000, v1
	v_pk_fma_f32 v[2:3], v[6:7], v[2:3], v[4:5]
	s_nop 0
	v_cvt_pk_bf16_f32 v147, v2, v3
	v_mul_f32_e32 v3, 0xbfb8aa3b, v10
	v_mul_f32_e32 v5, 0xbfb8aa3b, v11
	v_exp_f32_e32 v3, v3
	v_exp_f32_e32 v5, v5
	v_lshlrev_b32_e32 v2, 16, v146
	v_add_f32_e32 v3, 1.0, v3
	v_add_f32_e32 v5, 1.0, v5
	v_rcp_f32_e32 v4, v3
	v_rcp_f32_e32 v5, v5
	v_and_b32_e32 v3, 0xffff0000, v146
	v_pk_fma_f32 v[0:1], v[4:5], v[0:1], v[2:3]
	s_nop 0
	v_cvt_pk_bf16_f32 v146, v0, v1
	ds_read2st64_b32 v[0:1], v141 offset0:120 offset1:124
	v_lshlrev_b32_e32 v4, 16, v145
	v_and_b32_e32 v5, 0xffff0000, v145
	s_waitcnt lgkmcnt(0)
	v_lshlrev_b32_e32 v2, 16, v0
	v_and_b32_e32 v3, 0xffff0000, v0
	v_mul_f32_e32 v0, 0xbfb8aa3b, v12
	v_exp_f32_e32 v0, v0
	s_nop 0
	v_add_f32_e32 v0, 1.0, v0
	v_rcp_f32_e32 v6, v0
	v_mul_f32_e32 v0, 0xbfb8aa3b, v13
	v_exp_f32_e32 v0, v0
	s_nop 0
	v_add_f32_e32 v0, 1.0, v0
	v_rcp_f32_e32 v7, v0
	v_lshlrev_b32_e32 v0, 16, v1
	v_and_b32_e32 v1, 0xffff0000, v1
	v_pk_fma_f32 v[2:3], v[6:7], v[2:3], v[4:5]
	s_nop 0
	v_cvt_pk_bf16_f32 v145, v2, v3
	v_mul_f32_e32 v3, 0xbfb8aa3b, v14
	v_mul_f32_e32 v5, 0xbfb8aa3b, v15
	v_exp_f32_e32 v3, v3
	v_exp_f32_e32 v5, v5
	v_lshlrev_b32_e32 v2, 16, v144
	v_add_f32_e32 v3, 1.0, v3
	v_add_f32_e32 v5, 1.0, v5
	v_rcp_f32_e32 v4, v3
	v_rcp_f32_e32 v5, v5
	v_and_b32_e32 v3, 0xffff0000, v144
	v_pk_fma_f32 v[0:1], v[4:5], v[0:1], v[2:3]
	s_nop 0
	v_cvt_pk_bf16_f32 v144, v0, v1
	s_cbranch_scc0 .LBB0_871
	v_add_u32_e32 v0, s38, v142
	v_or_b32_e32 v2, s72, v143
	v_or_b32_e32 v6, 1, v0
	v_or_b32_e32 v8, 2, v0
	v_or_b32_e32 v10, 3, v0
	v_or_b32_e32 v12, 8, v0
	v_or_b32_e32 v14, 9, v0
	v_or_b32_e32 v16, 10, v0
	v_or_b32_e32 v18, 11, v0
	v_or_b32_e32 v20, 16, v0
	v_or_b32_e32 v22, 17, v0
	v_or_b32_e32 v24, 18, v0
	v_or_b32_e32 v26, 19, v0
	v_or_b32_e32 v28, 24, v0
	v_or_b32_e32 v30, 25, v0
	v_or_b32_e32 v32, 26, v0
	v_or_b32_e32 v34, 27, v0
	v_ashrrev_i32_e32 v3, 31, v2
	v_ashrrev_i32_e32 v1, 31, v0
	v_ashrrev_i32_e32 v7, 31, v6
	v_ashrrev_i32_e32 v9, 31, v8
	v_ashrrev_i32_e32 v11, 31, v10
	v_ashrrev_i32_e32 v13, 31, v12
	v_ashrrev_i32_e32 v15, 31, v14
	v_ashrrev_i32_e32 v17, 31, v16
	v_ashrrev_i32_e32 v19, 31, v18
	v_ashrrev_i32_e32 v21, 31, v20
	v_ashrrev_i32_e32 v23, 31, v22
	v_ashrrev_i32_e32 v25, 31, v24
	v_ashrrev_i32_e32 v27, 31, v26
	v_ashrrev_i32_e32 v29, 31, v28
	v_ashrrev_i32_e32 v31, 31, v30
	v_ashrrev_i32_e32 v33, 31, v32
	v_ashrrev_i32_e32 v35, 31, v34
	v_lshl_add_u64 v[2:3], v[2:3], 1, s[10:11]
	v_lshlrev_b64 v[4:5], 12, v[0:1]
	v_lshlrev_b64 v[6:7], 12, v[6:7]
	v_lshlrev_b64 v[8:9], 12, v[8:9]
	v_lshlrev_b64 v[10:11], 12, v[10:11]
	v_lshlrev_b64 v[12:13], 12, v[12:13]
	v_lshlrev_b64 v[14:15], 12, v[14:15]
	v_lshlrev_b64 v[16:17], 12, v[16:17]
	v_lshlrev_b64 v[18:19], 12, v[18:19]
	v_lshlrev_b64 v[20:21], 12, v[20:21]
	v_lshlrev_b64 v[22:23], 12, v[22:23]
	v_lshlrev_b64 v[24:25], 12, v[24:25]
	v_lshlrev_b64 v[26:27], 12, v[26:27]
	v_lshlrev_b64 v[28:29], 12, v[28:29]
	v_lshlrev_b64 v[30:31], 12, v[30:31]
	v_lshlrev_b64 v[32:33], 12, v[32:33]
	v_lshlrev_b64 v[34:35], 12, v[34:35]
	v_lshl_add_u64 v[4:5], v[2:3], 0, v[4:5]
	v_lshl_add_u64 v[6:7], v[2:3], 0, v[6:7]
	v_lshl_add_u64 v[8:9], v[2:3], 0, v[8:9]
	v_lshl_add_u64 v[10:11], v[2:3], 0, v[10:11]
	v_lshl_add_u64 v[12:13], v[2:3], 0, v[12:13]
	v_lshl_add_u64 v[14:15], v[2:3], 0, v[14:15]
	v_lshl_add_u64 v[16:17], v[2:3], 0, v[16:17]
	v_lshl_add_u64 v[18:19], v[2:3], 0, v[18:19]
	v_lshl_add_u64 v[20:21], v[2:3], 0, v[20:21]
	v_lshl_add_u64 v[22:23], v[2:3], 0, v[22:23]
	v_lshl_add_u64 v[24:25], v[2:3], 0, v[24:25]
	v_lshl_add_u64 v[26:27], v[2:3], 0, v[26:27]
	v_lshl_add_u64 v[28:29], v[2:3], 0, v[28:29]
	v_lshl_add_u64 v[30:31], v[2:3], 0, v[30:31]
	v_lshl_add_u64 v[32:33], v[2:3], 0, v[32:33]
	v_lshl_add_u64 v[34:35], v[2:3], 0, v[34:35]
	global_store_short v[4:5], v183, off
	global_store_short_d16_hi v[6:7], v183, off
	global_store_short v[8:9], v182, off
	global_store_short_d16_hi v[10:11], v182, off
	global_store_short v[12:13], v181, off
	global_store_short_d16_hi v[14:15], v181, off
	global_store_short v[16:17], v180, off
	global_store_short_d16_hi v[18:19], v180, off
	global_store_short v[20:21], v179, off
	global_store_short_d16_hi v[22:23], v179, off
	global_store_short v[24:25], v177, off
	global_store_short_d16_hi v[26:27], v177, off
	global_store_short v[28:29], v178, off
	global_store_short_d16_hi v[30:31], v178, off
	global_store_short v[32:33], v173, off
; DI int crow(int i, int h) { return (i & 3) + 8 * (i >> 2) + 4 * h; }
; DI void phase_merge(CP p, const Ptrs& w, int l, bf16_t* sA, bf16_t* sB, unsigned* sU) {
;     ...
;     bf16_t* dst = w.R2;
; #pragma unroll
;     for (int mi = 0; mi < 2; ++mi)
; #pragma unroll
;       for (int ni = 0; ni < 2; ++ni)
; #pragma unroll
;         for (int i = 0; i < 16; ++i) {
;           int row = m0 + wm * 64 + mi * 32 + crow(i, h), col = n0 + wn * 64 + ni * 32 + r;
;           const unsigned tv = totp[mi][ni][i >> 1];
;           dst[(size_t)row * 2048 + col] = (bf16_t)((i & 1) ? (tv >> 16) : (tv & 0xffffu));
;         }
;   }
	global_store_short_d16_hi v[34:35], v173, off
	global_store_short v[4:5], v176, off offset:64
	global_store_short_d16_hi v[6:7], v176, off offset:64
	global_store_short v[8:9], v170, off offset:64
	global_store_short_d16_hi v[10:11], v170, off offset:64
	global_store_short v[12:13], v175, off offset:64
	global_store_short_d16_hi v[14:15], v175, off offset:64
	global_store_short v[16:17], v174, off offset:64
	global_store_short_d16_hi v[18:19], v174, off offset:64
	global_store_short v[20:21], v172, off offset:64
	global_store_short_d16_hi v[22:23], v172, off offset:64
	global_store_short v[24:25], v171, off offset:64
	global_store_short_d16_hi v[26:27], v171, off offset:64
	global_store_short v[28:29], v169, off offset:64
	global_store_short_d16_hi v[30:31], v169, off offset:64
	global_store_short v[32:33], v168, off offset:64
	global_store_short_d16_hi v[34:35], v168, off offset:64
	v_or_b32_e32 v4, 32, v0
	v_or_b32_e32 v6, 33, v0
	v_or_b32_e32 v8, 34, v0
	v_or_b32_e32 v10, 35, v0
	v_or_b32_e32 v12, 40, v0
	v_or_b32_e32 v14, 41, v0
	v_or_b32_e32 v16, 42, v0
	v_or_b32_e32 v18, 43, v0
	v_or_b32_e32 v20, 48, v0
	v_or_b32_e32 v22, 49, v0
	v_or_b32_e32 v24, 50, v0
	v_or_b32_e32 v26, 51, v0
	v_or_b32_e32 v28, 56, v0
	v_or_b32_e32 v30, 57, v0
	v_or_b32_e32 v32, 58, v0
	v_or_b32_e32 v0, 59, v0
	v_ashrrev_i32_e32 v5, 31, v4
	v_ashrrev_i32_e32 v7, 31, v6
	v_ashrrev_i32_e32 v9, 31, v8
	v_ashrrev_i32_e32 v11, 31, v10
	v_ashrrev_i32_e32 v13, 31, v12
	v_ashrrev_i32_e32 v15, 31, v14
	v_ashrrev_i32_e32 v17, 31, v16
	v_ashrrev_i32_e32 v19, 31, v18
	v_ashrrev_i32_e32 v21, 31, v20
	v_ashrrev_i32_e32 v23, 31, v22
	v_ashrrev_i32_e32 v25, 31, v24
	v_ashrrev_i32_e32 v27, 31, v26
	v_ashrrev_i32_e32 v29, 31, v28
	v_ashrrev_i32_e32 v31, 31, v30
	v_ashrrev_i32_e32 v33, 31, v32
	v_ashrrev_i32_e32 v1, 31, v0
	v_lshlrev_b64 v[4:5], 12, v[4:5]
	v_lshlrev_b64 v[6:7], 12, v[6:7]
	v_lshlrev_b64 v[8:9], 12, v[8:9]
	v_lshlrev_b64 v[10:11], 12, v[10:11]
	v_lshlrev_b64 v[12:13], 12, v[12:13]
	v_lshlrev_b64 v[14:15], 12, v[14:15]
	v_lshlrev_b64 v[16:17], 12, v[16:17]
	v_lshlrev_b64 v[18:19], 12, v[18:19]
	v_lshlrev_b64 v[20:21], 12, v[20:21]
	v_lshlrev_b64 v[22:23], 12, v[22:23]
	v_lshlrev_b64 v[24:25], 12, v[24:25]
	v_lshlrev_b64 v[26:27], 12, v[26:27]
	v_lshlrev_b64 v[28:29], 12, v[28:29]
	v_lshlrev_b64 v[30:31], 12, v[30:31]
	v_lshlrev_b64 v[32:33], 12, v[32:33]
	v_lshlrev_b64 v[0:1], 12, v[0:1]
	v_lshl_add_u64 v[4:5], v[2:3], 0, v[4:5]
	v_lshl_add_u64 v[6:7], v[2:3], 0, v[6:7]
	v_lshl_add_u64 v[8:9], v[2:3], 0, v[8:9]
	v_lshl_add_u64 v[10:11], v[2:3], 0, v[10:11]
	v_lshl_add_u64 v[12:13], v[2:3], 0, v[12:13]
	v_lshl_add_u64 v[14:15], v[2:3], 0, v[14:15]
	v_lshl_add_u64 v[16:17], v[2:3], 0, v[16:17]
	v_lshl_add_u64 v[18:19], v[2:3], 0, v[18:19]
	v_lshl_add_u64 v[20:21], v[2:3], 0, v[20:21]
	v_lshl_add_u64 v[22:23], v[2:3], 0, v[22:23]
	v_lshl_add_u64 v[24:25], v[2:3], 0, v[24:25]
	v_lshl_add_u64 v[26:27], v[2:3], 0, v[26:27]
	v_lshl_add_u64 v[28:29], v[2:3], 0, v[28:29]
	v_lshl_add_u64 v[30:31], v[2:3], 0, v[30:31]
	v_lshl_add_u64 v[32:33], v[2:3], 0, v[32:33]
	v_lshl_add_u64 v[0:1], v[2:3], 0, v[0:1]
	global_store_short v[4:5], v167, off
	global_store_short_d16_hi v[6:7], v167, off
	global_store_short v[8:9], v164, off
	global_store_short_d16_hi v[10:11], v164, off
	global_store_short v[12:13], v163, off
	global_store_short_d16_hi v[14:15], v163, off
	global_store_short v[16:17], v161, off
	global_store_short_d16_hi v[18:19], v161, off
	global_store_short v[20:21], v155, off
	global_store_short_d16_hi v[22:23], v155, off
	global_store_short v[24:25], v154, off
	global_store_short_d16_hi v[26:27], v154, off
	global_store_short v[28:29], v153, off
	global_store_short_d16_hi v[30:31], v153, off
	global_store_short v[32:33], v152, off
	global_store_short_d16_hi v[0:1], v152, off
	global_store_short v[4:5], v151, off offset:64
	global_store_short_d16_hi v[6:7], v151, off offset:64
	global_store_short v[8:9], v150, off offset:64
	global_store_short_d16_hi v[10:11], v150, off offset:64
	global_store_short v[12:13], v149, off offset:64
	global_store_short_d16_hi v[14:15], v149, off offset:64
	global_store_short v[16:17], v148, off offset:64
	global_store_short_d16_hi v[18:19], v148, off offset:64
	global_store_short v[20:21], v147, off offset:64
	global_store_short_d16_hi v[22:23], v147, off offset:64
	global_store_short v[24:25], v146, off offset:64
	global_store_short_d16_hi v[26:27], v146, off offset:64
	global_store_short v[28:29], v145, off offset:64
	global_store_short_d16_hi v[30:31], v145, off offset:64
	global_store_short v[32:33], v144, off offset:64
	global_store_short_d16_hi v[0:1], v144, off offset:64
	s_add_i32 s69, s69, 1
	s_cmp_lg_u32 s69, s60
	s_mov_b32 s42, s71
	s_cbranch_scc1 .LBB0_861

; DI void gemm_128_deep(const bf16_t* __restrict__ A, int lda, const bf16_t* __restrict__ B, int ldb, int K, f32x16 (&acc)[2][2], bf16_t* sA, bf16_t* sBunused) {
;     ...
;   for (int k0 = 0; k0 < K - 256; k0 += 128) {
;     MMA_TILE(0)
;     ST_LDS(1, qa0, qa1, qa2, qa3, qb0, qb1, qb2, qb3)
;     GL_Q(k0 + 192)
;     __syncthreads();
;     MMA_TILE(1)
;     ST_LDS(0, pa0, pa1, pa2, pa3, pb0, pb1, pb2, pb3)
;     GL_P(k0 + 256)
;     __syncthreads();
;   }
.LBB0_954:
	ds_read_b128 v[152:155], v128
	ds_read_b128 v[168:171], v129 offset:18432
	ds_read_b128 v[172:175], v129 offset:23040
	s_mov_b32 s4, 0x1ba64000
	s_mov_b32 s38, 0x1a064000
	s_mov_b32 s6, 0x1baa4000
	s_waitcnt lgkmcnt(1)
	v_mfma_f32_32x32x16_bf16 v[48:63], v[152:155], v[168:171], v[48:63]
	s_mov_b32 s10, 0x1bac4000
	s_mov_b32 s40, 0x1a084000
	s_mov_b32 s42, 0x1a0a4000
	s_mov_b32 s44, 0x1a0c4000
	s_addk_i32 s47, 0x80
	s_cmpk_lt_u32 s47, 0x680
	s_waitcnt lgkmcnt(0)
	v_mfma_f32_32x32x16_bf16 v[32:47], v[152:155], v[172:175], v[32:47]
	ds_read_b128 v[152:155], v128 offset:4608
	s_waitcnt lgkmcnt(0)
	v_mfma_f32_32x32x16_bf16 v[16:31], v[152:155], v[168:171], v[16:31]
	v_mfma_f32_32x32x16_bf16 v[0:15], v[152:155], v[172:175], v[0:15]
	ds_read_b128 v[152:155], v128 offset:32
	ds_read_b128 v[168:171], v129 offset:18464
	ds_read_b128 v[172:175], v129 offset:23072
	s_waitcnt lgkmcnt(1)
	v_mfma_f32_32x32x16_bf16 v[48:63], v[152:155], v[168:171], v[48:63]
	s_waitcnt lgkmcnt(0)
	v_mfma_f32_32x32x16_bf16 v[32:47], v[152:155], v[172:175], v[32:47]
	ds_read_b128 v[152:155], v128 offset:4640
	s_waitcnt lgkmcnt(0)
	v_mfma_f32_32x32x16_bf16 v[16:31], v[152:155], v[168:171], v[16:31]
	ds_read_b128 v[168:171], v128 offset:64
	v_mfma_f32_32x32x16_bf16 v[0:15], v[152:155], v[172:175], v[0:15]
	ds_read_b128 v[176:179], v128 offset:4672
	ds_read_b128 v[172:175], v129 offset:18496
	ds_read_b128 v[194:197], v129 offset:23104
	ds_read_b128 v[198:201], v128 offset:96
	ds_read_b128 v[202:205], v128 offset:4704
	ds_read_b128 v[206:209], v129 offset:18528
	ds_read_b128 v[210:213], v129 offset:23136
	s_setprio 0
	s_waitcnt vmcnt(15)
	ds_write_b128 v130, v[108:111] offset:36864
	s_waitcnt vmcnt(14)
	ds_write_b128 v130, v[96:99] offset:41472
	s_waitcnt vmcnt(13)
	ds_write_b128 v130, v[100:103] offset:46080
	s_waitcnt vmcnt(12)
	ds_write_b128 v130, v[104:107] offset:50688
	s_waitcnt vmcnt(11)
	ds_write_b128 v130, v[112:115] offset:55296
	s_waitcnt vmcnt(10)
	ds_write_b128 v130, v[116:119] offset:59904
	s_waitcnt vmcnt(9)
	ds_write_b128 v130, v[120:123] offset:64512
	v_lshl_add_u64 v[96:97], v[150:151], 0, v[156:157]
	v_lshl_add_u64 v[98:99], v[148:149], 0, v[156:157]
	v_add_co_u32_e32 v152, vcc, s4, v96
	s_mov_b32 s4, 0x1ba84000
	s_waitcnt lgkmcnt(12)
	v_mfma_f32_32x32x16_bf16 v[48:63], v[168:171], v[172:175], v[48:63]
	s_waitcnt vmcnt(8)
	ds_write_b128 v131, v[124:127] offset:13824
	v_add_co_u32_e64 v154, s[4:5], s4, v96
	v_addc_co_u32_e32 v153, vcc, 0, v97, vcc
	s_nop 0
	v_addc_co_u32_e64 v155, vcc, 0, v97, s[4:5]
	s_waitcnt lgkmcnt(12)
	v_mfma_f32_32x32x16_bf16 v[32:47], v[168:171], v[194:197], v[32:47]
	v_add_co_u32_e64 v168, s[6:7], s6, v96
	v_add_co_u32_e64 v170, s[10:11], s10, v96
	s_nop 0
	v_addc_co_u32_e64 v169, vcc, 0, v97, s[6:7]
	v_addc_co_u32_e64 v171, vcc, 0, v97, s[10:11]
	v_mfma_f32_32x32x16_bf16 v[16:31], v[176:179], v[172:175], v[16:31]
	v_add_co_u32_e64 v172, s[38:39], s38, v98
	v_add_co_u32_e64 v174, s[40:41], s40, v98
	s_nop 0
	v_addc_co_u32_e64 v173, vcc, 0, v99, s[38:39]
	v_addc_co_u32_e64 v175, vcc, 0, v99, s[40:41]
	v_mfma_f32_32x32x16_bf16 v[0:15], v[176:179], v[194:197], v[0:15]
	v_add_co_u32_e64 v176, s[42:43], s42, v98
	v_add_co_u32_e64 v178, s[44:45], s44, v98
	s_nop 0
	v_addc_co_u32_e64 v177, vcc, 0, v99, s[42:43]
	v_addc_co_u32_e64 v179, vcc, 0, v99, s[44:45]
	s_waitcnt lgkmcnt(9)
	v_mfma_f32_32x32x16_bf16 v[48:63], v[198:201], v[206:209], v[48:63]
	global_load_dwordx4 v[108:111], v[152:153], off offset:2176
	global_load_dwordx4 v[96:99], v[154:155], off offset:2176
	global_load_dwordx4 v[100:103], v[168:169], off offset:2176
	global_load_dwordx4 v[104:107], v[170:171], off offset:2176
	global_load_dwordx4 v[112:115], v[172:173], off offset:2176
	global_load_dwordx4 v[116:119], v[174:175], off offset:2176
	global_load_dwordx4 v[120:123], v[176:177], off offset:2176
	global_load_dwordx4 v[124:127], v[178:179], off offset:2176
	s_waitcnt lgkmcnt(0)
	s_barrier
	s_setprio 1
	v_lshl_add_u64 v[148:149], v[148:149], 0, s[94:95]
	v_lshl_add_u64 v[150:151], v[150:151], 0, s[94:95]
	v_mfma_f32_32x32x16_bf16 v[32:47], v[198:201], v[210:213], v[32:47]
	ds_read_b128 v[194:197], v128 offset:36864
	ds_read_b128 v[198:201], v129 offset:55296
	v_mfma_f32_32x32x16_bf16 v[16:31], v[202:205], v[206:209], v[16:31]
	v_mfma_f32_32x32x16_bf16 v[0:15], v[202:205], v[210:213], v[0:15]
	ds_read_b128 v[202:205], v129 offset:59904
	s_waitcnt lgkmcnt(1)
	v_mfma_f32_32x32x16_bf16 v[48:63], v[194:197], v[198:201], v[48:63]
	s_waitcnt lgkmcnt(0)
	v_mfma_f32_32x32x16_bf16 v[32:47], v[194:197], v[202:205], v[32:47]
	ds_read_b128 v[194:197], v128 offset:41472
	s_waitcnt lgkmcnt(0)
	v_mfma_f32_32x32x16_bf16 v[16:31], v[194:197], v[198:201], v[16:31]
	v_mfma_f32_32x32x16_bf16 v[0:15], v[194:197], v[202:205], v[0:15]
	ds_read_b128 v[194:197], v128 offset:36896
	ds_read_b128 v[198:201], v129 offset:55328
	ds_read_b128 v[202:205], v129 offset:59936
	s_waitcnt lgkmcnt(1)
	v_mfma_f32_32x32x16_bf16 v[48:63], v[194:197], v[198:201], v[48:63]
	s_waitcnt lgkmcnt(0)
	v_mfma_f32_32x32x16_bf16 v[32:47], v[194:197], v[202:205], v[32:47]
	ds_read_b128 v[194:197], v128 offset:41504
	s_waitcnt lgkmcnt(0)
	v_mfma_f32_32x32x16_bf16 v[16:31], v[194:197], v[198:201], v[16:31]
	v_mfma_f32_32x32x16_bf16 v[0:15], v[194:197], v[202:205], v[0:15]
	ds_read_b128 v[194:197], v128 offset:36928
	ds_read_b128 v[198:201], v129 offset:55360
	ds_read_b128 v[202:205], v129 offset:59968
	s_waitcnt lgkmcnt(1)
	v_mfma_f32_32x32x16_bf16 v[48:63], v[194:197], v[198:201], v[48:63]
	s_waitcnt lgkmcnt(0)
	v_mfma_f32_32x32x16_bf16 v[32:47], v[194:197], v[202:205], v[32:47]
	ds_read_b128 v[194:197], v128 offset:41536
	s_waitcnt lgkmcnt(0)
	v_mfma_f32_32x32x16_bf16 v[16:31], v[194:197], v[198:201], v[16:31]
	v_mfma_f32_32x32x16_bf16 v[0:15], v[194:197], v[202:205], v[0:15]
	ds_read_b128 v[194:197], v128 offset:36960
	ds_read_b128 v[198:201], v129 offset:55392
	ds_read_b128 v[202:205], v128 offset:41568
	ds_read_b128 v[206:209], v129 offset:60000
	s_setprio 0
	s_waitcnt vmcnt(13)
	ds_write_b128 v130, v[92:95]
	ds_write_b128 v130, v[64:67] offset:4608
	ds_write_b128 v130, v[68:71] offset:9216
	s_waitcnt vmcnt(11)
	ds_write_b128 v130, v[84:87] offset:13824
	ds_write_b128 v130, v[72:75] offset:18432
	s_waitcnt vmcnt(10)
	ds_write_b128 v130, v[76:79] offset:23040
	s_waitcnt vmcnt(9)
	ds_write_b128 v130, v[80:83] offset:27648
	s_waitcnt vmcnt(8)
	ds_write_b128 v130, v[88:91] offset:32256
	global_load_dwordx4 v[92:95], v[152:153], off offset:2304
	global_load_dwordx4 v[64:67], v[154:155], off offset:2304
	global_load_dwordx4 v[68:71], v[168:169], off offset:2304
	global_load_dwordx4 v[84:87], v[170:171], off offset:2304
	global_load_dwordx4 v[72:75], v[172:173], off offset:2304
	global_load_dwordx4 v[76:79], v[174:175], off offset:2304
	global_load_dwordx4 v[80:83], v[176:177], off offset:2304
	global_load_dwordx4 v[88:91], v[178:179], off offset:2304
	s_waitcnt lgkmcnt(0)
	s_barrier
; DI void gemm_128_deep(const bf16_t* __restrict__ A, int lda, const bf16_t* __restrict__ B, int ldb, int K, f32x16 (&acc)[2][2], bf16_t* sA, bf16_t* sBunused) {
;     ...
;   for (int k0 = 0; k0 < K - 256; k0 += 128) {
;     MMA_TILE(0)
;     ST_LDS(1, qa0, qa1, qa2, qa3, qb0, qb1, qb2, qb3)
;     GL_Q(k0 + 192)
;     __syncthreads();
;     MMA_TILE(1)
;     ST_LDS(0, pa0, pa1, pa2, pa3, pb0, pb1, pb2, pb3)
;     GL_P(k0 + 256)
;     __syncthreads();
;   }
;   MMA_TILE(0)
;   ST_LDS(1, qa0, qa1, qa2, qa3, qb0, qb1, qb2, qb3)
;   GL_Q(K - 64)
;   __syncthreads();
;   MMA_TILE(1)
;   ST_LDS(0, pa0, pa1, pa2, pa3, pb0, pb1, pb2, pb3)
;   __syncthreads();
;   MMA_TILE(0)
;   ST_LDS(1, qa0, qa1, qa2, qa3, qb0, qb1, qb2, qb3)
;   __syncthreads();
;   MMA_TILE(1)
;   __syncthreads();
	s_setprio 1
	v_mfma_f32_32x32x16_bf16 v[48:63], v[194:197], v[198:201], v[48:63]
	v_mfma_f32_32x32x16_bf16 v[32:47], v[194:197], v[206:209], v[32:47]
	v_mfma_f32_32x32x16_bf16 v[16:31], v[202:205], v[198:201], v[16:31]
	v_mfma_f32_32x32x16_bf16 v[0:15], v[202:205], v[206:209], v[0:15]
	s_cbranch_scc1 .LBB0_954
	s_setprio 0
	ds_read_b128 v[148:151], v128
	ds_read_b128 v[152:155], v129 offset:18432
	ds_read_b128 v[168:171], v129 offset:23040
	s_mul_hi_i32 s4, s90, 0x3e0f83e1
	s_lshr_b32 s5, s4, 31
	s_ashr_i32 s39, s4, 4
	s_waitcnt lgkmcnt(1)
	v_mfma_f32_32x32x16_bf16 v[48:63], v[148:151], v[152:155], v[48:63]
	s_add_i32 s39, s39, s5
	s_mul_i32 s38, s39, 0x2100
	s_sub_i32 s10, s48, s38
	s_cmpk_lt_i32 s10, 0x100
	s_cselect_b64 s[4:5], -1, 0
	s_and_b64 s[6:7], s[4:5], exec
	s_cselect_b32 s6, 2, s39
	s_waitcnt lgkmcnt(0)
	v_mfma_f32_32x32x16_bf16 v[32:47], v[148:151], v[168:171], v[32:47]
	ds_read_b128 v[148:151], v128 offset:4608
	v_readlane_b32 s7, v254, 56
	s_add_i32 s6, s6, s7
	s_mulk_i32 s6, 0x1800
	s_ashr_i32 s7, s6, 31
	s_lshl_b64 s[6:7], s[6:7], 2
	s_add_u32 s6, s78, s6
	s_waitcnt lgkmcnt(0)
	v_mfma_f32_32x32x16_bf16 v[16:31], v[148:151], v[152:155], v[16:31]
	s_addc_u32 s7, s79, s7
	s_add_u32 s6, s6, 0x4000
	s_addc_u32 s7, s7, 0
	v_readlane_b32 s40, v254, 54
	v_readlane_b32 s41, v254, 55
	s_and_b64 vcc, exec, s[40:41]
	v_mfma_f32_32x32x16_bf16 v[0:15], v[148:151], v[168:171], v[0:15]
	ds_read_b128 v[148:151], v128 offset:32
	ds_read_b128 v[152:155], v129 offset:18464
	ds_read_b128 v[168:171], v129 offset:23072
	s_waitcnt lgkmcnt(1)
	v_mfma_f32_32x32x16_bf16 v[48:63], v[148:151], v[152:155], v[48:63]
	s_waitcnt lgkmcnt(0)
	v_mfma_f32_32x32x16_bf16 v[32:47], v[148:151], v[168:171], v[32:47]
	ds_read_b128 v[148:151], v128 offset:4640
	s_waitcnt lgkmcnt(0)
	v_mfma_f32_32x32x16_bf16 v[16:31], v[148:151], v[152:155], v[16:31]
	v_mfma_f32_32x32x16_bf16 v[0:15], v[148:151], v[168:171], v[0:15]
	ds_read_b128 v[148:151], v128 offset:64
	ds_read_b128 v[152:155], v129 offset:18496
	ds_read_b128 v[168:171], v129 offset:23104
	s_waitcnt lgkmcnt(1)
	v_mfma_f32_32x32x16_bf16 v[48:63], v[148:151], v[152:155], v[48:63]
	s_waitcnt lgkmcnt(0)
	v_mfma_f32_32x32x16_bf16 v[32:47], v[148:151], v[168:171], v[32:47]
	ds_read_b128 v[148:151], v128 offset:4672
	s_waitcnt lgkmcnt(0)
	v_mfma_f32_32x32x16_bf16 v[16:31], v[148:151], v[152:155], v[16:31]
	v_mfma_f32_32x32x16_bf16 v[0:15], v[148:151], v[168:171], v[0:15]
	ds_read_b128 v[148:151], v128 offset:96
	ds_read_b128 v[152:155], v129 offset:18528
	ds_read_b128 v[168:171], v129 offset:23136
	s_waitcnt lgkmcnt(1)
	v_mfma_f32_32x32x16_bf16 v[48:63], v[148:151], v[152:155], v[48:63]
	s_waitcnt lgkmcnt(0)
	v_mfma_f32_32x32x16_bf16 v[32:47], v[148:151], v[168:171], v[32:47]
	ds_read_b128 v[148:151], v128 offset:4704
	s_waitcnt vmcnt(15)
	ds_write_b128 v130, v[108:111] offset:36864
	s_waitcnt vmcnt(14)
	ds_write_b128 v130, v[96:99] offset:41472
	s_waitcnt vmcnt(13)
	ds_write_b128 v130, v[100:103] offset:46080
	s_waitcnt vmcnt(12)
	ds_write_b128 v130, v[104:107] offset:50688
	s_waitcnt vmcnt(11)
	ds_write_b128 v130, v[112:115] offset:55296
	s_waitcnt vmcnt(10)
	ds_write_b128 v130, v[116:119] offset:59904
	s_waitcnt vmcnt(9)
	ds_write_b128 v130, v[120:123] offset:64512
	s_waitcnt vmcnt(8)
	ds_write_b128 v131, v[124:127] offset:13824
	global_load_dwordx4 v[96:99], v[142:143], off offset:3968
	global_load_dwordx4 v[100:103], v[138:139], off offset:3968
	global_load_dwordx4 v[104:107], v[144:145], off offset:3968
	global_load_dwordx4 v[108:111], v[146:147], off offset:3968
	global_load_dwordx4 v[112:115], v[132:133], off offset:3968
	global_load_dwordx4 v[116:119], v[134:135], off offset:3968
	global_load_dwordx4 v[120:123], v[136:137], off offset:3968
	global_load_dwordx4 v[124:127], v[140:141], off offset:3968
	s_waitcnt lgkmcnt(0)
	s_barrier
	ds_read_b128 v[132:135], v128 offset:36864
	ds_read_b128 v[136:139], v129 offset:55296
	ds_read_b128 v[140:143], v129 offset:59904
	s_waitcnt lgkmcnt(1)
	v_mfma_f32_32x32x16_bf16 v[48:63], v[132:135], v[136:139], v[48:63]
	s_waitcnt lgkmcnt(0)
	v_mfma_f32_32x32x16_bf16 v[32:47], v[132:135], v[140:143], v[32:47]
	ds_read_b128 v[132:135], v128 offset:41472
	v_mfma_f32_32x32x16_bf16 v[16:31], v[148:151], v[152:155], v[16:31]
	v_mfma_f32_32x32x16_bf16 v[0:15], v[148:151], v[168:171], v[0:15]
	s_waitcnt lgkmcnt(0)
	v_mfma_f32_32x32x16_bf16 v[16:31], v[132:135], v[136:139], v[16:31]
	v_mfma_f32_32x32x16_bf16 v[0:15], v[132:135], v[140:143], v[0:15]
	ds_read_b128 v[132:135], v128 offset:36896
	ds_read_b128 v[136:139], v129 offset:55328
	ds_read_b128 v[140:143], v129 offset:59936
	s_waitcnt lgkmcnt(1)
	v_mfma_f32_32x32x16_bf16 v[48:63], v[132:135], v[136:139], v[48:63]
	s_waitcnt lgkmcnt(0)
	v_mfma_f32_32x32x16_bf16 v[32:47], v[132:135], v[140:143], v[32:47]
	ds_read_b128 v[132:135], v128 offset:41504
	s_waitcnt lgkmcnt(0)
	v_mfma_f32_32x32x16_bf16 v[16:31], v[132:135], v[136:139], v[16:31]
	v_mfma_f32_32x32x16_bf16 v[0:15], v[132:135], v[140:143], v[0:15]
	ds_read_b128 v[132:135], v128 offset:36928
	ds_read_b128 v[136:139], v129 offset:55360
	ds_read_b128 v[140:143], v129 offset:59968
	s_waitcnt lgkmcnt(1)
	v_mfma_f32_32x32x16_bf16 v[48:63], v[132:135], v[136:139], v[48:63]
	s_waitcnt lgkmcnt(0)
	v_mfma_f32_32x32x16_bf16 v[32:47], v[132:135], v[140:143], v[32:47]
	ds_read_b128 v[132:135], v128 offset:41536
	s_waitcnt lgkmcnt(0)
	v_mfma_f32_32x32x16_bf16 v[16:31], v[132:135], v[136:139], v[16:31]
	v_mfma_f32_32x32x16_bf16 v[0:15], v[132:135], v[140:143], v[0:15]
	ds_read_b128 v[132:135], v128 offset:36960
	ds_read_b128 v[136:139], v129 offset:55392
	ds_read_b128 v[140:143], v129 offset:60000
	s_waitcnt lgkmcnt(1)
	v_mfma_f32_32x32x16_bf16 v[48:63], v[132:135], v[136:139], v[48:63]
	s_waitcnt lgkmcnt(0)
	v_mfma_f32_32x32x16_bf16 v[32:47], v[132:135], v[140:143], v[32:47]
	ds_read_b128 v[132:135], v128 offset:41568
	s_waitcnt vmcnt(15)
	ds_write_b128 v130, v[92:95]
	s_waitcnt vmcnt(14)
	ds_write_b128 v130, v[64:67] offset:4608
	s_waitcnt vmcnt(13)
	ds_write_b128 v130, v[68:71] offset:9216
	s_waitcnt vmcnt(12)
	ds_write_b128 v130, v[84:87] offset:13824
	s_waitcnt vmcnt(11)
	ds_write_b128 v130, v[72:75] offset:18432
	s_waitcnt vmcnt(10)
	ds_write_b128 v130, v[76:79] offset:23040
	s_waitcnt vmcnt(9)
	ds_write_b128 v130, v[80:83] offset:27648
	s_waitcnt vmcnt(8)
	ds_write_b128 v130, v[88:91] offset:32256
	s_waitcnt lgkmcnt(0)
	s_barrier
; DI int crow(int i, int h) { return (i & 3) + 8 * (i >> 2) + 4 * h; }
; DI void gemm_128_deep(const bf16_t* __restrict__ A, int lda, const bf16_t* __restrict__ B, int ldb, int K, f32x16 (&acc)[2][2], bf16_t* sA, bf16_t* sBunused) {
;     ...
;   MMA_TILE(1)
;   ST_LDS(0, pa0, pa1, pa2, pa3, pb0, pb1, pb2, pb3)
;   __syncthreads();
;   MMA_TILE(0)
;   ST_LDS(1, qa0, qa1, qa2, qa3, qb0, qb1, qb2, qb3)
;   __syncthreads();
;   MMA_TILE(1)
;   __syncthreads();
; DI void phase_out(CP p, const Ptrs& w, int l, bf16_t* sA, bf16_t* sB) {
;     ...
;     int b = m0 / TPB, ib = m0 - b * TPB;
;     bool isctx = ib < CTXL;
;     f32x16 acc[2][2];
;     zero_acc(acc);
;     gemm_128_deep(w.R2 + (size_t)m0 * 2048, 2048, out_t + (size_t)n0 * 2048, 2048, 2048, acc, sA, sB);
;     const float* gate = w.mod + (l * 3 + (isctx ? 2 : b)) * 6144 + 4096;
; #pragma unroll
;     for (int mi = 0; mi < 2; ++mi)
; #pragma unroll
;       for (int ni = 0; ni < 2; ++ni) {
;         int col = n0 + wn * 64 + ni * 32 + r;
;         float gt = gate[col];
; #pragma unroll
;         for (int i = 0; i < 16; ++i) {
;           int ii = ib + wm * 64 + mi * 32 + crow(i, h);
;           const float* src = xrow(p, w, l, b * TPB + ii);
;           float* dstp = isctx ? w.xc1 + (size_t)(b * CTXL + ii) * DM : p.out + (size_t)(b * 8192 + ii - CTXL) * DM;
;           dstp[col] = src[col] + gt * acc[mi][ni][i];
	ds_read_b128 v[64:67], v128
	ds_read_b128 v[68:71], v129 offset:18432
	ds_read_b128 v[72:75], v129 offset:23040
	s_waitcnt lgkmcnt(1)
	v_mfma_f32_32x32x16_bf16 v[48:63], v[64:67], v[68:71], v[48:63]
	v_add_u32_e32 v92, s10, v163
	s_mov_b64 s[10:11], -1
	s_waitcnt lgkmcnt(0)
	v_mfma_f32_32x32x16_bf16 v[32:47], v[64:67], v[72:75], v[32:47]
	ds_read_b128 v[64:67], v128 offset:4608
	v_mfma_f32_32x32x16_bf16 v[16:31], v[132:135], v[136:139], v[16:31]
	v_mfma_f32_32x32x16_bf16 v[0:15], v[132:135], v[140:143], v[0:15]
	s_waitcnt lgkmcnt(0)
	v_mfma_f32_32x32x16_bf16 v[16:31], v[64:67], v[68:71], v[16:31]
	v_mfma_f32_32x32x16_bf16 v[0:15], v[64:67], v[72:75], v[0:15]
	ds_read_b128 v[64:67], v128 offset:32
	ds_read_b128 v[68:71], v129 offset:18464
	ds_read_b128 v[72:75], v129 offset:23072
	s_waitcnt lgkmcnt(1)
	v_mfma_f32_32x32x16_bf16 v[48:63], v[64:67], v[68:71], v[48:63]
	s_waitcnt lgkmcnt(0)
	v_mfma_f32_32x32x16_bf16 v[32:47], v[64:67], v[72:75], v[32:47]
	ds_read_b128 v[64:67], v128 offset:4640
	s_waitcnt lgkmcnt(0)
	v_mfma_f32_32x32x16_bf16 v[16:31], v[64:67], v[68:71], v[16:31]
	v_mfma_f32_32x32x16_bf16 v[0:15], v[64:67], v[72:75], v[0:15]
	ds_read_b128 v[64:67], v128 offset:64
	ds_read_b128 v[68:71], v129 offset:18496
	ds_read_b128 v[72:75], v129 offset:23104
	s_waitcnt lgkmcnt(1)
	v_mfma_f32_32x32x16_bf16 v[48:63], v[64:67], v[68:71], v[48:63]
	s_waitcnt lgkmcnt(0)
	v_mfma_f32_32x32x16_bf16 v[32:47], v[64:67], v[72:75], v[32:47]
	ds_read_b128 v[64:67], v128 offset:4672
	s_waitcnt lgkmcnt(0)
	v_mfma_f32_32x32x16_bf16 v[16:31], v[64:67], v[68:71], v[16:31]
	v_mfma_f32_32x32x16_bf16 v[0:15], v[64:67], v[72:75], v[0:15]
	ds_read_b128 v[64:67], v128 offset:96
	ds_read_b128 v[68:71], v129 offset:18528
	ds_read_b128 v[72:75], v129 offset:23136
	s_waitcnt lgkmcnt(1)
	v_mfma_f32_32x32x16_bf16 v[48:63], v[64:67], v[68:71], v[48:63]
	s_waitcnt lgkmcnt(0)
	v_mfma_f32_32x32x16_bf16 v[32:47], v[64:67], v[72:75], v[32:47]
	ds_read_b128 v[64:67], v128 offset:4704
	s_waitcnt vmcnt(7)
	ds_write_b128 v130, v[96:99] offset:36864
	s_waitcnt vmcnt(6)
	ds_write_b128 v130, v[100:103] offset:41472
	s_waitcnt vmcnt(5)
	ds_write_b128 v130, v[104:107] offset:46080
	s_waitcnt vmcnt(4)
	ds_write_b128 v130, v[108:111] offset:50688
	s_waitcnt vmcnt(3)
	ds_write_b128 v130, v[112:115] offset:55296
	s_waitcnt vmcnt(2)
	ds_write_b128 v130, v[116:119] offset:59904
	s_waitcnt vmcnt(1)
	ds_write_b128 v130, v[120:123] offset:64512
	s_waitcnt vmcnt(0)
	ds_write_b128 v131, v[124:127] offset:13824
	s_waitcnt lgkmcnt(0)
	s_barrier
	v_mfma_f32_32x32x16_bf16 v[16:31], v[64:67], v[68:71], v[16:31]
	v_mfma_f32_32x32x16_bf16 v[0:15], v[64:67], v[72:75], v[0:15]
	ds_read_b128 v[64:67], v128 offset:36864
	ds_read_b128 v[68:71], v129 offset:55296
	ds_read_b128 v[72:75], v129 offset:59904
	s_waitcnt lgkmcnt(1)
	v_mfma_f32_32x32x16_bf16 v[48:63], v[64:67], v[68:71], v[48:63]
	s_waitcnt lgkmcnt(0)
	v_mfma_f32_32x32x16_bf16 v[32:47], v[64:67], v[72:75], v[32:47]
	ds_read_b128 v[64:67], v128 offset:41472
	s_waitcnt lgkmcnt(0)
	v_mfma_f32_32x32x16_bf16 v[16:31], v[64:67], v[68:71], v[16:31]
	v_mfma_f32_32x32x16_bf16 v[0:15], v[64:67], v[72:75], v[0:15]
	ds_read_b128 v[64:67], v128 offset:36896
	ds_read_b128 v[68:71], v129 offset:55328
	ds_read_b128 v[72:75], v129 offset:59936
	s_waitcnt lgkmcnt(1)
	v_mfma_f32_32x32x16_bf16 v[48:63], v[64:67], v[68:71], v[48:63]
	s_waitcnt lgkmcnt(0)
	v_mfma_f32_32x32x16_bf16 v[32:47], v[64:67], v[72:75], v[32:47]
	ds_read_b128 v[64:67], v128 offset:41504
	s_waitcnt lgkmcnt(0)
	v_mfma_f32_32x32x16_bf16 v[16:31], v[64:67], v[68:71], v[16:31]
	v_mfma_f32_32x32x16_bf16 v[0:15], v[64:67], v[72:75], v[0:15]
	ds_read_b128 v[64:67], v128 offset:36928
	ds_read_b128 v[68:71], v129 offset:55360
	ds_read_b128 v[72:75], v129 offset:59968
	s_waitcnt lgkmcnt(1)
	v_mfma_f32_32x32x16_bf16 v[48:63], v[64:67], v[68:71], v[48:63]
	s_waitcnt lgkmcnt(0)
	v_mfma_f32_32x32x16_bf16 v[32:47], v[64:67], v[72:75], v[32:47]
	ds_read_b128 v[64:67], v128 offset:41536
	s_waitcnt lgkmcnt(0)
	v_mfma_f32_32x32x16_bf16 v[16:31], v[64:67], v[68:71], v[16:31]
	ds_read_b128 v[68:71], v128 offset:36960
	ds_read_b128 v[76:79], v128 offset:41568
	ds_read_b128 v[80:83], v129 offset:55392
	ds_read_b128 v[84:87], v129 offset:60000
	s_waitcnt lgkmcnt(0)
	s_barrier
	v_mfma_f32_32x32x16_bf16 v[0:15], v[64:67], v[72:75], v[0:15]
	v_or_b32_e32 v64, s46, v161
	v_ashrrev_i32_e32 v65, 31, v64
	v_or_b32_e32 v72, v92, v164
	v_add_u32_e32 v66, s38, v72
	v_mul_hi_i32 v67, v66, s0
	v_mfma_f32_32x32x16_bf16 v[48:63], v[68:71], v[80:83], v[48:63]
	v_mfma_f32_32x32x16_bf16 v[32:47], v[68:71], v[84:87], v[32:47]
	v_lshl_add_u64 v[68:69], v[64:65], 2, s[6:7]
	global_load_dword v90, v[68:69], off
	v_lshrrev_b32_e32 v70, 31, v67
	v_ashrrev_i32_e32 v67, 11, v67
	v_add_u32_e32 v93, v67, v70
	v_mad_i32_i24 v94, v93, s1, v66
	v_cmp_lt_i32_e64 s[42:43], s37, v94
	v_mfma_f32_32x32x16_bf16 v[16:31], v[76:79], v[80:83], v[16:31]
	v_mfma_f32_32x32x16_bf16 v[0:15], v[76:79], v[84:87], v[0:15]
	s_cbranch_vccz .LBB0_961
	s_and_saveexec_b64 s[10:11], s[42:43]
	s_xor_b64 s[10:11], exec, s[10:11]
	v_lshlrev_b32_e32 v66, 13, v93
	s_movk_i32 s40, 0xff00
	v_add3_u32 v66, v66, v94, s40
	s_or_saveexec_b64 s[10:11], s[10:11]
	v_mov_b64_e32 v[70:71], s[76:77]
	s_xor_b64 exec, exec, s[10:11]
	v_lshl_add_u32 v66, v93, 8, v94
	v_mov_b64_e32 v[70:71], s[12:13]
	s_or_b64 exec, exec, s[10:11]
	s_mov_b64 s[10:11], 0
